# static prio (waves 0-3) + saddr-form LDS-DMA (SALU bases, no 64-bit VALU address math) in 7 more GEMM K-loops (P2,P3,P6,P10,P12,P18,P22)
# speedup vs baseline: 1.0082x; 1.0018x over previous
; #define PG8_STAGE(bufoff, gbase, voff) do { _Pragma("unroll") for (int _i = 0; _i < 2; ++_i) \
;         __builtin_amdgcn_global_load_lds((const unsigned*)((const char*)(gbase) + (voff)[_i]), (PG8_LAS unsigned*)(lds + (bufoff) + ldsw + _i * 8192), 16, 0, 0); } while (0)
; #define PG8_LDA(dst, b, h) do { _Pragma("unroll") for (int m = 0; m < 4; ++m) _Pragma("unroll") for (int k = 0; k < 2; ++k) dst[m][k] = *(const PG8_LAS bf16x8*)(lds + PG8_SA(b, h) + aoff + m * 2048 + k * 1024); } while (0)
; #define PG8_LDB(dst, b, h) do { _Pragma("unroll") for (int n = 0; n < 2; ++n) _Pragma("unroll") for (int k = 0; k < 2; ++k) dst[n][k] = *(const PG8_LAS bf16x8*)(lds + PG8_SB(b, h) + boff + n * 2048 + k * 1024); } while (0)
; #define PG8_MMA(ai, bj, At, Bt) do { __builtin_amdgcn_s_setprio(1); _Pragma("unroll") for (int m = 0; m < 4; ++m) _Pragma("unroll") for (int n = 0; n < 2; ++n) _Pragma("unroll") for (int k = 0; k < 2; ++k) \
;         acc[ai][bj][m][n] = __builtin_amdgcn_mfma_f32_16x16x32_bf16(Bt[n][k], At[m][k], acc[ai][bj][m][n], 0, 0, 0); __builtin_amdgcn_s_setprio(0); } while (0)
; #define PG8_WAIT_V(n) asm volatile("s_waitcnt vmcnt(" #n ")" ::: "memory")
; #define PG8_WAIT_L(n) asm volatile("s_waitcnt lgkmcnt(" #n ")" ::: "memory")
; #define PG8_BAR __builtin_amdgcn_s_barrier()
; #define PG8_SCHED __builtin_amdgcn_sched_barrier(0)
; template <class Epi, class Sched, bool ALIGN_EPI = false>
; __device__ __forceinline__ void gemm_phase(PG8_LAS unsigned char* lds, const Gemm g, const Sched& S, const Epi& E) {
;     ...
;             PG8_LDB(B0, 0, 0); PG8_LDB(B1, 0, 1); PG8_SCHED; PG8_LDA(At, 0, 0); PG8_STAGE(PG8_SA(1, 1), a1 + hstepA, voffA);
;             PG8_WAIT_V(8); PG8_WAIT_L(0); PG8_BAR; PG8_MMA(0, 0, At, B0); PG8_MMA(0, 1, At, B1); PG8_BAR; PG8_SCHED;
;             PG8_LDA(At, 0, 1); PG8_STAGE(PG8_SB(0, 0), b2, voffB); PG8_STAGE(PG8_SB(0, 1), b2 + hstepB, voffB); PG8_STAGE(PG8_SA(0, 0), a2, voffA);
;             PG8_WAIT_V(8); PG8_WAIT_L(0); PG8_BAR; PG8_MMA(1, 0, At, B0); PG8_MMA(1, 1, At, B1); PG8_BAR; PG8_SCHED;
.LBB0_198:
	s_waitcnt vmcnt(0)
	ds_read_b128 v[42:45], v172
	ds_read_b128 v[46:49], v172 offset:1024
	ds_read_b128 v[50:53], v172 offset:2048
	ds_read_b128 v[58:61], v172 offset:3072
	ds_read_b128 v[164:167], v173
	ds_read_b128 v[168:171], v173 offset:1024
	ds_read_b128 v[176:179], v173 offset:2048
	ds_read_b128 v[180:183], v173 offset:3072
	s_add_u32 s8, s6, 0xfff00080
	s_addc_u32 s9, s7, -1
	s_cmp_eq_u32 s63, 60
	s_cselect_b32 s41, s5, s9
	s_cselect_b32 s40, s14, s8
	s_cselect_b32 s9, s31, s62
	s_cselect_b32 s8, s35, s61
	s_add_i32 m0, s13, 0xc000
	ds_read_b128 v[184:187], v174
	ds_read_b128 v[188:191], v174 offset:1024
	ds_read_b128 v[192:195], v174 offset:2048
	ds_read_b128 v[196:199], v174 offset:3072
	ds_read_b128 v[200:203], v174 offset:4096
	ds_read_b128 v[204:207], v174 offset:5120
	ds_read_b128 v[208:211], v174 offset:6144
	ds_read_b128 v[212:215], v174 offset:7168
	global_load_lds_dwordx4 v156, s[6:7]
	s_add_i32 m0, s13, 0xe000
	s_nop 0
	global_load_lds_dwordx4 v158, s[6:7]
	s_waitcnt vmcnt(8)
	s_waitcnt lgkmcnt(0)
	s_barrier
	s_waitcnt lgkmcnt(0)
	v_mfma_f32_16x16x32_bf16 v[142:145], v[42:45], v[184:187], v[142:145]
	v_mfma_f32_16x16x32_bf16 v[138:141], v[50:53], v[184:187], v[138:141]
	v_mfma_f32_16x16x32_bf16 v[126:129], v[42:45], v[192:195], v[126:129]
	v_mfma_f32_16x16x32_bf16 v[122:125], v[50:53], v[192:195], v[122:125]
	v_mfma_f32_16x16x32_bf16 v[110:113], v[42:45], v[200:203], v[110:113]
	v_mfma_f32_16x16x32_bf16 v[106:109], v[50:53], v[200:203], v[106:109]
	v_mfma_f32_16x16x32_bf16 v[94:97], v[42:45], v[208:211], v[94:97]
	v_mfma_f32_16x16x32_bf16 v[90:93], v[50:53], v[208:211], v[90:93]
	v_mfma_f32_16x16x32_bf16 v[142:145], v[46:49], v[188:191], v[142:145]
	v_mfma_f32_16x16x32_bf16 v[138:141], v[58:61], v[188:191], v[138:141]
	v_mfma_f32_16x16x32_bf16 v[126:129], v[46:49], v[196:199], v[126:129]
	v_mfma_f32_16x16x32_bf16 v[122:125], v[58:61], v[196:199], v[122:125]
	v_mfma_f32_16x16x32_bf16 v[110:113], v[46:49], v[204:207], v[110:113]
	v_mfma_f32_16x16x32_bf16 v[106:109], v[58:61], v[204:207], v[106:109]
	v_mfma_f32_16x16x32_bf16 v[94:97], v[46:49], v[212:215], v[94:97]
	v_mfma_f32_16x16x32_bf16 v[90:93], v[58:61], v[212:215], v[90:93]
	v_mfma_f32_16x16x32_bf16 v[134:137], v[164:167], v[184:187], v[134:137]
	v_mfma_f32_16x16x32_bf16 v[130:133], v[176:179], v[184:187], v[130:133]
	v_mfma_f32_16x16x32_bf16 v[118:121], v[164:167], v[192:195], v[118:121]
	v_mfma_f32_16x16x32_bf16 v[114:117], v[176:179], v[192:195], v[114:117]
	v_mfma_f32_16x16x32_bf16 v[102:105], v[164:167], v[200:203], v[102:105]
	v_mfma_f32_16x16x32_bf16 v[98:101], v[176:179], v[200:203], v[98:101]
	v_mfma_f32_16x16x32_bf16 v[86:89], v[164:167], v[208:211], v[86:89]
	v_mfma_f32_16x16x32_bf16 v[82:85], v[176:179], v[208:211], v[82:85]
	v_mfma_f32_16x16x32_bf16 v[134:137], v[168:171], v[188:191], v[134:137]
	v_mfma_f32_16x16x32_bf16 v[130:133], v[180:183], v[188:191], v[130:133]
	v_mfma_f32_16x16x32_bf16 v[118:121], v[168:171], v[196:199], v[118:121]
	v_mfma_f32_16x16x32_bf16 v[114:117], v[180:183], v[196:199], v[114:117]
	v_mfma_f32_16x16x32_bf16 v[102:105], v[168:171], v[204:207], v[102:105]
	v_mfma_f32_16x16x32_bf16 v[98:101], v[180:183], v[204:207], v[98:101]
	v_mfma_f32_16x16x32_bf16 v[86:89], v[168:171], v[212:215], v[86:89]
	v_mfma_f32_16x16x32_bf16 v[82:85], v[180:183], v[212:215], v[82:85]
	s_barrier
	s_add_i32 s64, s53, s46
	s_add_u32 s98, s8, s24
	s_addc_u32 s99, s9, s25
	s_mov_b32 m0, s64
	ds_read_b128 v[184:187], v174 offset:16384
	ds_read_b128 v[188:191], v174 offset:17408
	ds_read_b128 v[192:195], v174 offset:18432
	ds_read_b128 v[196:199], v174 offset:19456
	ds_read_b128 v[200:203], v174 offset:20480
	ds_read_b128 v[204:207], v174 offset:21504
	ds_read_b128 v[208:211], v174 offset:22528
	ds_read_b128 v[212:215], v174 offset:23552
	global_load_lds_dwordx4 v148, s[8:9]
	s_add_i32 m0, s64, 0x2000
	s_add_u32 s64, s8, 0x100000
	s_addc_u32 s65, s9, 0
	s_add_i32 s66, s54, s46
	global_load_lds_dwordx4 v152, s[8:9]
	s_mov_b32 m0, s66
	s_nop 0
	global_load_lds_dwordx4 v148, s[64:65]
	s_add_i32 m0, s66, 0x2000
	s_nop 0
	global_load_lds_dwordx4 v152, s[64:65]
	s_add_u32 s100, s40, s24
	s_addc_u32 s101, s41, s25
	s_mov_b32 m0, s13
	s_nop 0
	global_load_lds_dwordx4 v146, s[40:41]
	s_mov_b32 m0, s47
	s_nop 0
	global_load_lds_dwordx4 v150, s[40:41]
	s_waitcnt vmcnt(8)
	s_waitcnt lgkmcnt(0)
	s_barrier
	s_waitcnt lgkmcnt(0)
	v_mfma_f32_16x16x32_bf16 v[78:81], v[42:45], v[184:187], v[78:81]
	v_mfma_f32_16x16x32_bf16 v[74:77], v[50:53], v[184:187], v[74:77]
	v_mfma_f32_16x16x32_bf16 v[62:65], v[42:45], v[192:195], v[62:65]
	v_mfma_f32_16x16x32_bf16 v[54:57], v[50:53], v[192:195], v[54:57]
	v_mfma_f32_16x16x32_bf16 v[30:33], v[42:45], v[200:203], v[30:33]
	v_mfma_f32_16x16x32_bf16 v[26:29], v[50:53], v[200:203], v[26:29]
	v_mfma_f32_16x16x32_bf16 v[14:17], v[42:45], v[208:211], v[14:17]
	v_mfma_f32_16x16x32_bf16 v[10:13], v[50:53], v[208:211], v[10:13]
	v_mfma_f32_16x16x32_bf16 v[78:81], v[46:49], v[188:191], v[78:81]
	v_mfma_f32_16x16x32_bf16 v[74:77], v[58:61], v[188:191], v[74:77]
	v_mfma_f32_16x16x32_bf16 v[62:65], v[46:49], v[196:199], v[62:65]
	v_mfma_f32_16x16x32_bf16 v[54:57], v[58:61], v[196:199], v[54:57]
	v_mfma_f32_16x16x32_bf16 v[30:33], v[46:49], v[204:207], v[30:33]
	v_mfma_f32_16x16x32_bf16 v[26:29], v[58:61], v[204:207], v[26:29]
	v_mfma_f32_16x16x32_bf16 v[14:17], v[46:49], v[212:215], v[14:17]
	v_mfma_f32_16x16x32_bf16 v[10:13], v[58:61], v[212:215], v[10:13]
	v_mfma_f32_16x16x32_bf16 v[38:41], v[164:167], v[192:195], v[38:41]
	v_mfma_f32_16x16x32_bf16 v[34:37], v[176:179], v[192:195], v[34:37]
	v_mfma_f32_16x16x32_bf16 v[22:25], v[164:167], v[200:203], v[22:25]
	v_mfma_f32_16x16x32_bf16 v[18:21], v[176:179], v[200:203], v[18:21]
	v_mfma_f32_16x16x32_bf16 v[6:9], v[164:167], v[208:211], v[6:9]
	v_mfma_f32_16x16x32_bf16 v[2:5], v[176:179], v[208:211], v[2:5]
	v_mfma_f32_16x16x32_bf16 v[42:45], v[164:167], v[184:187], v[70:73]
	v_mfma_f32_16x16x32_bf16 v[46:49], v[176:179], v[184:187], v[66:69]
	v_mfma_f32_16x16x32_bf16 v[38:41], v[168:171], v[196:199], v[38:41]
	v_mfma_f32_16x16x32_bf16 v[34:37], v[180:183], v[196:199], v[34:37]
	v_mfma_f32_16x16x32_bf16 v[22:25], v[168:171], v[204:207], v[22:25]
	v_mfma_f32_16x16x32_bf16 v[18:21], v[180:183], v[204:207], v[18:21]
	v_mfma_f32_16x16x32_bf16 v[6:9], v[168:171], v[212:215], v[6:9]
	v_mfma_f32_16x16x32_bf16 v[2:5], v[180:183], v[212:215], v[2:5]
	v_mfma_f32_16x16x32_bf16 v[42:45], v[168:171], v[188:191], v[42:45]
	v_mfma_f32_16x16x32_bf16 v[46:49], v[180:183], v[188:191], v[46:49]
	s_barrier
; #define PG8_STAGE(bufoff, gbase, voff) do { _Pragma("unroll") for (int _i = 0; _i < 2; ++_i) \
;         __builtin_amdgcn_global_load_lds((const unsigned*)((const char*)(gbase) + (voff)[_i]), (PG8_LAS unsigned*)(lds + (bufoff) + ldsw + _i * 8192), 16, 0, 0); } while (0)
; #define PG8_LDA(dst, b, h) do { _Pragma("unroll") for (int m = 0; m < 4; ++m) _Pragma("unroll") for (int k = 0; k < 2; ++k) dst[m][k] = *(const PG8_LAS bf16x8*)(lds + PG8_SA(b, h) + aoff + m * 2048 + k * 1024); } while (0)
; #define PG8_LDB(dst, b, h) do { _Pragma("unroll") for (int n = 0; n < 2; ++n) _Pragma("unroll") for (int k = 0; k < 2; ++k) dst[n][k] = *(const PG8_LAS bf16x8*)(lds + PG8_SB(b, h) + boff + n * 2048 + k * 1024); } while (0)
; #define PG8_MMA(ai, bj, At, Bt) do { __builtin_amdgcn_s_setprio(1); _Pragma("unroll") for (int m = 0; m < 4; ++m) _Pragma("unroll") for (int n = 0; n < 2; ++n) _Pragma("unroll") for (int k = 0; k < 2; ++k) \
;         acc[ai][bj][m][n] = __builtin_amdgcn_mfma_f32_16x16x32_bf16(Bt[n][k], At[m][k], acc[ai][bj][m][n], 0, 0, 0); __builtin_amdgcn_s_setprio(0); } while (0)
; #define PG8_WAIT_V(n) asm volatile("s_waitcnt vmcnt(" #n ")" ::: "memory")
; #define PG8_WAIT_L(n) asm volatile("s_waitcnt lgkmcnt(" #n ")" ::: "memory")
; #define PG8_BAR __builtin_amdgcn_s_barrier()
; #define PG8_SCHED __builtin_amdgcn_sched_barrier(0)
; template <class Epi, class Sched, bool ALIGN_EPI = false>
; __device__ __forceinline__ void gemm_phase(PG8_LAS unsigned char* lds, const Gemm g, const Sched& S, const Epi& E) {
;     ...
;             PG8_LDB(B0, 1, 0); PG8_LDB(B1, 1, 1); PG8_SCHED; PG8_LDA(At, 1, 0); PG8_STAGE(PG8_SA(0, 1), a2 + hstepA, voffA);
;             PG8_WAIT_V(8); PG8_WAIT_L(0); PG8_BAR; PG8_MMA(0, 0, At, B0); PG8_MMA(0, 1, At, B1); PG8_BAR; PG8_SCHED;
;             PG8_LDA(At, 1, 1); PG8_STAGE(PG8_SB(1, 0), b3, voffB); PG8_STAGE(PG8_SB(1, 1), b3 + hstepB, voffB); PG8_STAGE(PG8_SA(1, 0), a3, voffA);
;             PG8_WAIT_V(8); PG8_WAIT_L(0); PG8_BAR; PG8_MMA(1, 0, At, B0); PG8_MMA(1, 1, At, B1); PG8_BAR; PG8_SCHED;
;         }
;         if constexpr (ALIGN_EPI) { if (wr == 0) PG8_BAR; }
	s_add_i32 s64, 0, 0x18000
	s_add_i32 s65, 0, 0x1c000
	v_add_u32_e32 v70, s64, v1
	v_add_u32_e32 v154, s65, v1
	ds_read_b128 v[50:53], v70
	ds_read_b128 v[58:61], v70 offset:1024
	ds_read_b128 v[66:69], v70 offset:2048
	ds_read_b128 v[70:73], v70 offset:3072
	ds_read_b128 v[164:167], v154
	ds_read_b128 v[168:171], v154 offset:1024
	ds_read_b128 v[176:179], v154 offset:2048
	ds_read_b128 v[180:183], v154 offset:3072
	s_add_u32 s40, s40, 0x100000
	s_addc_u32 s41, s41, 0
	s_mov_b32 m0, s48
	ds_read_b128 v[184:187], v174 offset:32768
	ds_read_b128 v[188:191], v174 offset:33792
	ds_read_b128 v[192:195], v174 offset:34816
	ds_read_b128 v[196:199], v174 offset:35840
	ds_read_b128 v[200:203], v174 offset:36864
	ds_read_b128 v[204:207], v174 offset:37888
	ds_read_b128 v[208:211], v174 offset:38912
	ds_read_b128 v[212:215], v174 offset:39936
	global_load_lds_dwordx4 v146, s[40:41]
	s_mov_b32 m0, s49
	s_nop 0
	global_load_lds_dwordx4 v150, s[40:41]
	s_waitcnt vmcnt(8)
	s_waitcnt lgkmcnt(0)
	s_barrier
	s_waitcnt lgkmcnt(0)
	v_mfma_f32_16x16x32_bf16 v[142:145], v[50:53], v[184:187], v[142:145]
	v_mfma_f32_16x16x32_bf16 v[138:141], v[66:69], v[184:187], v[138:141]
	v_mfma_f32_16x16x32_bf16 v[126:129], v[50:53], v[192:195], v[126:129]
	v_mfma_f32_16x16x32_bf16 v[122:125], v[66:69], v[192:195], v[122:125]
	v_mfma_f32_16x16x32_bf16 v[110:113], v[50:53], v[200:203], v[110:113]
	v_mfma_f32_16x16x32_bf16 v[106:109], v[66:69], v[200:203], v[106:109]
	v_mfma_f32_16x16x32_bf16 v[94:97], v[50:53], v[208:211], v[94:97]
	v_mfma_f32_16x16x32_bf16 v[90:93], v[66:69], v[208:211], v[90:93]
	v_mfma_f32_16x16x32_bf16 v[142:145], v[58:61], v[188:191], v[142:145]
	v_mfma_f32_16x16x32_bf16 v[138:141], v[70:73], v[188:191], v[138:141]
	v_mfma_f32_16x16x32_bf16 v[126:129], v[58:61], v[196:199], v[126:129]
	v_mfma_f32_16x16x32_bf16 v[122:125], v[70:73], v[196:199], v[122:125]
	v_mfma_f32_16x16x32_bf16 v[110:113], v[58:61], v[204:207], v[110:113]
	v_mfma_f32_16x16x32_bf16 v[106:109], v[70:73], v[204:207], v[106:109]
	v_mfma_f32_16x16x32_bf16 v[94:97], v[58:61], v[212:215], v[94:97]
	v_mfma_f32_16x16x32_bf16 v[90:93], v[70:73], v[212:215], v[90:93]
	v_mfma_f32_16x16x32_bf16 v[134:137], v[164:167], v[184:187], v[134:137]
	v_mfma_f32_16x16x32_bf16 v[130:133], v[176:179], v[184:187], v[130:133]
	v_mfma_f32_16x16x32_bf16 v[118:121], v[164:167], v[192:195], v[118:121]
	v_mfma_f32_16x16x32_bf16 v[114:117], v[176:179], v[192:195], v[114:117]
	v_mfma_f32_16x16x32_bf16 v[102:105], v[164:167], v[200:203], v[102:105]
	v_mfma_f32_16x16x32_bf16 v[98:101], v[176:179], v[200:203], v[98:101]
	v_mfma_f32_16x16x32_bf16 v[86:89], v[164:167], v[208:211], v[86:89]
	v_mfma_f32_16x16x32_bf16 v[82:85], v[176:179], v[208:211], v[82:85]
	v_mfma_f32_16x16x32_bf16 v[134:137], v[168:171], v[188:191], v[134:137]
	v_mfma_f32_16x16x32_bf16 v[130:133], v[180:183], v[188:191], v[130:133]
	v_mfma_f32_16x16x32_bf16 v[118:121], v[168:171], v[196:199], v[118:121]
	v_mfma_f32_16x16x32_bf16 v[114:117], v[180:183], v[196:199], v[114:117]
	v_mfma_f32_16x16x32_bf16 v[102:105], v[168:171], v[204:207], v[102:105]
	v_mfma_f32_16x16x32_bf16 v[98:101], v[180:183], v[204:207], v[98:101]
	v_mfma_f32_16x16x32_bf16 v[86:89], v[168:171], v[212:215], v[86:89]
	v_mfma_f32_16x16x32_bf16 v[82:85], v[180:183], v[212:215], v[82:85]
	s_barrier
	s_add_i32 s40, s64, s46
	s_mov_b32 m0, s40
	ds_read_b128 v[184:187], v174 offset:49152
	ds_read_b128 v[188:191], v174 offset:50176
	ds_read_b128 v[192:195], v174 offset:51200
	ds_read_b128 v[196:199], v174 offset:52224
	ds_read_b128 v[200:203], v174 offset:53248
	ds_read_b128 v[204:207], v174 offset:54272
	ds_read_b128 v[208:211], v174 offset:55296
	ds_read_b128 v[212:215], v174 offset:56320
	global_load_lds_dwordx4 v148, s[98:99]
	s_add_i32 m0, s40, 0x2000
	s_add_u32 s8, s8, 0x100080
	s_addc_u32 s9, s9, 0
	s_add_i32 s40, s65, s46
	global_load_lds_dwordx4 v152, s[98:99]
	s_mov_b32 m0, s40
	s_nop 0
	global_load_lds_dwordx4 v148, s[8:9]
	s_add_i32 m0, s40, 0x2000
	s_nop 0
	global_load_lds_dwordx4 v152, s[8:9]
	s_mov_b32 m0, s0
	s_nop 0
	global_load_lds_dwordx4 v146, s[100:101]
	s_mov_b32 m0, s1
	s_nop 0
	global_load_lds_dwordx4 v150, s[100:101]
	s_waitcnt vmcnt(8)
	s_waitcnt lgkmcnt(0)
	s_barrier
	s_waitcnt lgkmcnt(0)
	v_mfma_f32_16x16x32_bf16 v[78:81], v[50:53], v[184:187], v[78:81]
	v_mfma_f32_16x16x32_bf16 v[74:77], v[66:69], v[184:187], v[74:77]
	v_mfma_f32_16x16x32_bf16 v[62:65], v[50:53], v[192:195], v[62:65]
	v_mfma_f32_16x16x32_bf16 v[54:57], v[66:69], v[192:195], v[54:57]
	v_mfma_f32_16x16x32_bf16 v[30:33], v[50:53], v[200:203], v[30:33]
	v_mfma_f32_16x16x32_bf16 v[26:29], v[66:69], v[200:203], v[26:29]
	v_mfma_f32_16x16x32_bf16 v[14:17], v[50:53], v[208:211], v[14:17]
	v_mfma_f32_16x16x32_bf16 v[10:13], v[66:69], v[208:211], v[10:13]
	v_mfma_f32_16x16x32_bf16 v[78:81], v[58:61], v[188:191], v[78:81]
	v_mfma_f32_16x16x32_bf16 v[74:77], v[70:73], v[188:191], v[74:77]
	v_mfma_f32_16x16x32_bf16 v[62:65], v[58:61], v[196:199], v[62:65]
	v_mfma_f32_16x16x32_bf16 v[54:57], v[70:73], v[196:199], v[54:57]
	v_mfma_f32_16x16x32_bf16 v[30:33], v[58:61], v[204:207], v[30:33]
	v_mfma_f32_16x16x32_bf16 v[26:29], v[70:73], v[204:207], v[26:29]
	v_mfma_f32_16x16x32_bf16 v[14:17], v[58:61], v[212:215], v[14:17]
	v_mfma_f32_16x16x32_bf16 v[10:13], v[70:73], v[212:215], v[10:13]
	v_mfma_f32_16x16x32_bf16 v[42:45], v[164:167], v[184:187], v[42:45]
	v_mfma_f32_16x16x32_bf16 v[70:73], v[168:171], v[188:191], v[42:45]
	v_mfma_f32_16x16x32_bf16 v[42:45], v[176:179], v[184:187], v[46:49]
	v_mfma_f32_16x16x32_bf16 v[38:41], v[164:167], v[192:195], v[38:41]
	v_mfma_f32_16x16x32_bf16 v[34:37], v[176:179], v[192:195], v[34:37]
	v_mfma_f32_16x16x32_bf16 v[22:25], v[164:167], v[200:203], v[22:25]
	v_mfma_f32_16x16x32_bf16 v[18:21], v[176:179], v[200:203], v[18:21]
	v_mfma_f32_16x16x32_bf16 v[6:9], v[164:167], v[208:211], v[6:9]
	v_mfma_f32_16x16x32_bf16 v[2:5], v[176:179], v[208:211], v[2:5]
	v_mfma_f32_16x16x32_bf16 v[66:69], v[180:183], v[188:191], v[42:45]
	v_mfma_f32_16x16x32_bf16 v[38:41], v[168:171], v[196:199], v[38:41]
	v_mfma_f32_16x16x32_bf16 v[34:37], v[180:183], v[196:199], v[34:37]
	v_mfma_f32_16x16x32_bf16 v[22:25], v[168:171], v[204:207], v[22:25]
	v_mfma_f32_16x16x32_bf16 v[18:21], v[180:183], v[204:207], v[18:21]
	v_mfma_f32_16x16x32_bf16 v[6:9], v[168:171], v[212:215], v[6:9]
	v_mfma_f32_16x16x32_bf16 v[2:5], v[180:183], v[212:215], v[2:5]
	s_barrier
	s_add_i32 s63, s63, 2
	s_add_u32 s6, s6, 0x100
	s_addc_u32 s7, s7, 0
	s_add_u32 s61, s61, 0x100
	s_addc_u32 s62, s62, 0
	s_cmp_gt_u32 s63, 61
	s_cbranch_scc0 .LBB0_198
	s_and_b64 vcc, exec, s[26:27]
	s_cbranch_vccz .LBB0_201
	s_barrier

; #define PG8_STAGE(bufoff, gbase, voff) do { _Pragma("unroll") for (int _i = 0; _i < 2; ++_i) \
;         __builtin_amdgcn_global_load_lds((const unsigned*)((const char*)(gbase) + (voff)[_i]), (PG8_LAS unsigned*)(lds + (bufoff) + ldsw + _i * 8192), 16, 0, 0); } while (0)
; #define PG8_LDA(dst, b, h) do { _Pragma("unroll") for (int m = 0; m < 4; ++m) _Pragma("unroll") for (int k = 0; k < 2; ++k) dst[m][k] = *(const PG8_LAS bf16x8*)(lds + PG8_SA(b, h) + aoff + m * 2048 + k * 1024); } while (0)
; #define PG8_LDB(dst, b, h) do { _Pragma("unroll") for (int n = 0; n < 2; ++n) _Pragma("unroll") for (int k = 0; k < 2; ++k) dst[n][k] = *(const PG8_LAS bf16x8*)(lds + PG8_SB(b, h) + boff + n * 2048 + k * 1024); } while (0)
; #define PG8_MMA(ai, bj, At, Bt) do { __builtin_amdgcn_s_setprio(1); _Pragma("unroll") for (int m = 0; m < 4; ++m) _Pragma("unroll") for (int n = 0; n < 2; ++n) _Pragma("unroll") for (int k = 0; k < 2; ++k) \
;         acc[ai][bj][m][n] = __builtin_amdgcn_mfma_f32_16x16x32_bf16(Bt[n][k], At[m][k], acc[ai][bj][m][n], 0, 0, 0); __builtin_amdgcn_s_setprio(0); } while (0)
; #define PG8_WAIT_V(n) asm volatile("s_waitcnt vmcnt(" #n ")" ::: "memory")
; #define PG8_WAIT_L(n) asm volatile("s_waitcnt lgkmcnt(" #n ")" ::: "memory")
; #define PG8_BAR __builtin_amdgcn_s_barrier()
; #define PG8_SCHED __builtin_amdgcn_sched_barrier(0)
; template <class Epi, class Sched, bool ALIGN_EPI = false>
; __device__ __forceinline__ void gemm_phase(PG8_LAS unsigned char* lds, const Gemm g, const Sched& S, const Epi& E) {
;     ...
;             PG8_LDB(B0, 0, 0); PG8_LDB(B1, 0, 1); PG8_SCHED; PG8_LDA(At, 0, 0); PG8_STAGE(PG8_SA(1, 1), a1 + hstepA, voffA);
;             PG8_WAIT_V(8); PG8_WAIT_L(0); PG8_BAR; PG8_MMA(0, 0, At, B0); PG8_MMA(0, 1, At, B1); PG8_BAR; PG8_SCHED;
;             PG8_LDA(At, 0, 1); PG8_STAGE(PG8_SB(0, 0), b2, voffB); PG8_STAGE(PG8_SB(0, 1), b2 + hstepB, voffB); PG8_STAGE(PG8_SA(0, 0), a2, voffA);
;             PG8_WAIT_V(8); PG8_WAIT_L(0); PG8_BAR; PG8_MMA(1, 0, At, B0); PG8_MMA(1, 1, At, B1); PG8_BAR; PG8_SCHED;
.LBB0_393:
	ds_read_b128 v[148:151], v144
	ds_read_b128 v[152:155], v144 offset:1024
	ds_read_b128 v[156:159], v144 offset:2048
	ds_read_b128 v[160:163], v144 offset:3072
	ds_read_b128 v[164:167], v145
	ds_read_b128 v[168:171], v145 offset:1024
	ds_read_b128 v[172:175], v145 offset:2048
	ds_read_b128 v[176:179], v145 offset:3072
	s_add_u32 s36, s34, 0xfff00080
	s_addc_u32 s37, s35, -1
	s_cmp_eq_u32 s66, 60
	s_cselect_b32 s39, s25, s37
	s_cselect_b32 s38, s62, s36
	s_cselect_b32 s37, s23, s65
	s_cselect_b32 s36, s63, s64
	s_add_i32 m0, s31, 0xc000
	ds_read_b128 v[180:183], v146
	ds_read_b128 v[184:187], v146 offset:1024
	ds_read_b128 v[188:191], v146 offset:2048
	ds_read_b128 v[192:195], v146 offset:3072
	ds_read_b128 v[196:199], v146 offset:4096
	ds_read_b128 v[200:203], v146 offset:5120
	ds_read_b128 v[204:207], v146 offset:6144
	ds_read_b128 v[208:211], v146 offset:7168
	global_load_lds_dwordx4 v138, s[34:35]
	s_add_i32 m0, s31, 0xe000
	s_nop 0
	global_load_lds_dwordx4 v140, s[34:35]
	s_waitcnt vmcnt(8)
	s_waitcnt lgkmcnt(0)
	s_barrier
	s_waitcnt lgkmcnt(0)
	v_mfma_f32_16x16x32_bf16 v[126:129], v[148:151], v[180:183], v[126:129]
	v_mfma_f32_16x16x32_bf16 v[122:125], v[156:159], v[180:183], v[122:125]
	v_mfma_f32_16x16x32_bf16 v[118:121], v[148:151], v[188:191], v[118:121]
	v_mfma_f32_16x16x32_bf16 v[110:113], v[156:159], v[188:191], v[110:113]
	v_mfma_f32_16x16x32_bf16 v[102:105], v[148:151], v[196:199], v[102:105]
	v_mfma_f32_16x16x32_bf16 v[94:97], v[156:159], v[196:199], v[94:97]
	v_mfma_f32_16x16x32_bf16 v[86:89], v[148:151], v[204:207], v[86:89]
	v_mfma_f32_16x16x32_bf16 v[78:81], v[156:159], v[204:207], v[78:81]
	v_mfma_f32_16x16x32_bf16 v[126:129], v[152:155], v[184:187], v[126:129]
	v_mfma_f32_16x16x32_bf16 v[122:125], v[160:163], v[184:187], v[122:125]
	v_mfma_f32_16x16x32_bf16 v[118:121], v[152:155], v[192:195], v[118:121]
	v_mfma_f32_16x16x32_bf16 v[110:113], v[160:163], v[192:195], v[110:113]
	v_mfma_f32_16x16x32_bf16 v[102:105], v[152:155], v[200:203], v[102:105]
	v_mfma_f32_16x16x32_bf16 v[94:97], v[160:163], v[200:203], v[94:97]
	v_mfma_f32_16x16x32_bf16 v[86:89], v[152:155], v[208:211], v[86:89]
	v_mfma_f32_16x16x32_bf16 v[78:81], v[160:163], v[208:211], v[78:81]
	v_mfma_f32_16x16x32_bf16 v[114:117], v[164:167], v[180:183], v[114:117]
	v_mfma_f32_16x16x32_bf16 v[106:109], v[172:175], v[180:183], v[106:109]
	v_mfma_f32_16x16x32_bf16 v[98:101], v[164:167], v[188:191], v[98:101]
	v_mfma_f32_16x16x32_bf16 v[90:93], v[172:175], v[188:191], v[90:93]
	v_mfma_f32_16x16x32_bf16 v[82:85], v[164:167], v[196:199], v[82:85]
	v_mfma_f32_16x16x32_bf16 v[74:77], v[172:175], v[196:199], v[74:77]
	v_mfma_f32_16x16x32_bf16 v[70:73], v[164:167], v[204:207], v[70:73]
	v_mfma_f32_16x16x32_bf16 v[66:69], v[172:175], v[204:207], v[66:69]
	v_mfma_f32_16x16x32_bf16 v[114:117], v[168:171], v[184:187], v[114:117]
	v_mfma_f32_16x16x32_bf16 v[106:109], v[176:179], v[184:187], v[106:109]
	v_mfma_f32_16x16x32_bf16 v[98:101], v[168:171], v[192:195], v[98:101]
	v_mfma_f32_16x16x32_bf16 v[90:93], v[176:179], v[192:195], v[90:93]
	v_mfma_f32_16x16x32_bf16 v[82:85], v[168:171], v[200:203], v[82:85]
	v_mfma_f32_16x16x32_bf16 v[74:77], v[176:179], v[200:203], v[74:77]
	v_mfma_f32_16x16x32_bf16 v[70:73], v[168:171], v[208:211], v[70:73]
	v_mfma_f32_16x16x32_bf16 v[66:69], v[176:179], v[208:211], v[66:69]
	s_barrier
	s_add_i32 s67, s51, s43
	s_add_u32 s98, s36, s8
	s_addc_u32 s99, s37, s9
	s_mov_b32 m0, s67
	ds_read_b128 v[180:183], v146 offset:16384
	ds_read_b128 v[184:187], v146 offset:17408
	ds_read_b128 v[188:191], v146 offset:18432
	ds_read_b128 v[192:195], v146 offset:19456
	ds_read_b128 v[196:199], v146 offset:20480
	ds_read_b128 v[200:203], v146 offset:21504
	ds_read_b128 v[204:207], v146 offset:22528
	ds_read_b128 v[208:211], v146 offset:23552
	global_load_lds_dwordx4 v132, s[36:37]
	s_add_i32 m0, s67, 0x2000
	s_add_u32 s68, s36, 0x100000
	s_addc_u32 s69, s37, 0
	s_add_i32 s67, s52, s43
	global_load_lds_dwordx4 v136, s[36:37]
	s_mov_b32 m0, s67
	s_nop 0
	global_load_lds_dwordx4 v132, s[68:69]
	s_add_i32 m0, s67, 0x2000
	s_nop 0
	global_load_lds_dwordx4 v136, s[68:69]
	s_add_u32 s100, s38, s8
	s_addc_u32 s101, s39, s9
	s_mov_b32 m0, s31
	s_nop 0
	global_load_lds_dwordx4 v130, s[38:39]
	s_mov_b32 m0, s44
	s_nop 0
	global_load_lds_dwordx4 v134, s[38:39]
	s_waitcnt vmcnt(8)
	s_waitcnt lgkmcnt(0)
	s_barrier
	s_waitcnt lgkmcnt(0)
	v_mfma_f32_16x16x32_bf16 v[62:65], v[148:151], v[180:183], v[62:65]
	v_mfma_f32_16x16x32_bf16 v[58:61], v[156:159], v[180:183], v[58:61]
	v_mfma_f32_16x16x32_bf16 v[54:57], v[148:151], v[188:191], v[54:57]
	v_mfma_f32_16x16x32_bf16 v[46:49], v[156:159], v[188:191], v[46:49]
	v_mfma_f32_16x16x32_bf16 v[38:41], v[148:151], v[196:199], v[38:41]
	v_mfma_f32_16x16x32_bf16 v[30:33], v[156:159], v[196:199], v[30:33]
	v_mfma_f32_16x16x32_bf16 v[22:25], v[148:151], v[204:207], v[22:25]
	v_mfma_f32_16x16x32_bf16 v[14:17], v[156:159], v[204:207], v[14:17]
	v_mfma_f32_16x16x32_bf16 v[62:65], v[152:155], v[184:187], v[62:65]
	v_mfma_f32_16x16x32_bf16 v[58:61], v[160:163], v[184:187], v[58:61]
	v_mfma_f32_16x16x32_bf16 v[54:57], v[152:155], v[192:195], v[54:57]
	v_mfma_f32_16x16x32_bf16 v[46:49], v[160:163], v[192:195], v[46:49]
	v_mfma_f32_16x16x32_bf16 v[38:41], v[152:155], v[200:203], v[38:41]
	v_mfma_f32_16x16x32_bf16 v[30:33], v[160:163], v[200:203], v[30:33]
	v_mfma_f32_16x16x32_bf16 v[22:25], v[152:155], v[208:211], v[22:25]
	v_mfma_f32_16x16x32_bf16 v[14:17], v[160:163], v[208:211], v[14:17]
	v_mfma_f32_16x16x32_bf16 v[50:53], v[164:167], v[180:183], v[50:53]
	v_mfma_f32_16x16x32_bf16 v[42:45], v[172:175], v[180:183], v[42:45]
	v_mfma_f32_16x16x32_bf16 v[34:37], v[164:167], v[188:191], v[34:37]
	v_mfma_f32_16x16x32_bf16 v[26:29], v[172:175], v[188:191], v[26:29]
	v_mfma_f32_16x16x32_bf16 v[18:21], v[164:167], v[196:199], v[18:21]
	v_mfma_f32_16x16x32_bf16 v[10:13], v[172:175], v[196:199], v[10:13]
	v_mfma_f32_16x16x32_bf16 v[6:9], v[164:167], v[204:207], v[6:9]
	v_mfma_f32_16x16x32_bf16 v[2:5], v[172:175], v[204:207], v[2:5]
	v_mfma_f32_16x16x32_bf16 v[50:53], v[168:171], v[184:187], v[50:53]
	v_mfma_f32_16x16x32_bf16 v[42:45], v[176:179], v[184:187], v[42:45]
	v_mfma_f32_16x16x32_bf16 v[34:37], v[168:171], v[192:195], v[34:37]
	v_mfma_f32_16x16x32_bf16 v[26:29], v[176:179], v[192:195], v[26:29]
	v_mfma_f32_16x16x32_bf16 v[18:21], v[168:171], v[200:203], v[18:21]
	v_mfma_f32_16x16x32_bf16 v[10:13], v[176:179], v[200:203], v[10:13]
	v_mfma_f32_16x16x32_bf16 v[6:9], v[168:171], v[208:211], v[6:9]
	v_mfma_f32_16x16x32_bf16 v[2:5], v[176:179], v[208:211], v[2:5]
	s_barrier
; #define PG8_STAGE(bufoff, gbase, voff) do { _Pragma("unroll") for (int _i = 0; _i < 2; ++_i) \
;         __builtin_amdgcn_global_load_lds((const unsigned*)((const char*)(gbase) + (voff)[_i]), (PG8_LAS unsigned*)(lds + (bufoff) + ldsw + _i * 8192), 16, 0, 0); } while (0)
; #define PG8_LDA(dst, b, h) do { _Pragma("unroll") for (int m = 0; m < 4; ++m) _Pragma("unroll") for (int k = 0; k < 2; ++k) dst[m][k] = *(const PG8_LAS bf16x8*)(lds + PG8_SA(b, h) + aoff + m * 2048 + k * 1024); } while (0)
; #define PG8_LDB(dst, b, h) do { _Pragma("unroll") for (int n = 0; n < 2; ++n) _Pragma("unroll") for (int k = 0; k < 2; ++k) dst[n][k] = *(const PG8_LAS bf16x8*)(lds + PG8_SB(b, h) + boff + n * 2048 + k * 1024); } while (0)
; #define PG8_MMA(ai, bj, At, Bt) do { __builtin_amdgcn_s_setprio(1); _Pragma("unroll") for (int m = 0; m < 4; ++m) _Pragma("unroll") for (int n = 0; n < 2; ++n) _Pragma("unroll") for (int k = 0; k < 2; ++k) \
;         acc[ai][bj][m][n] = __builtin_amdgcn_mfma_f32_16x16x32_bf16(Bt[n][k], At[m][k], acc[ai][bj][m][n], 0, 0, 0); __builtin_amdgcn_s_setprio(0); } while (0)
; #define PG8_WAIT_V(n) asm volatile("s_waitcnt vmcnt(" #n ")" ::: "memory")
; #define PG8_WAIT_L(n) asm volatile("s_waitcnt lgkmcnt(" #n ")" ::: "memory")
; #define PG8_BAR __builtin_amdgcn_s_barrier()
; #define PG8_SCHED __builtin_amdgcn_sched_barrier(0)
; template <class Epi, class Sched, bool ALIGN_EPI = false>
; __device__ __forceinline__ void gemm_phase(PG8_LAS unsigned char* lds, const Gemm g, const Sched& S, const Epi& E) {
;     ...
;             PG8_LDB(B0, 1, 0); PG8_LDB(B1, 1, 1); PG8_SCHED; PG8_LDA(At, 1, 0); PG8_STAGE(PG8_SA(0, 1), a2 + hstepA, voffA);
;             PG8_WAIT_V(8); PG8_WAIT_L(0); PG8_BAR; PG8_MMA(0, 0, At, B0); PG8_MMA(0, 1, At, B1); PG8_BAR; PG8_SCHED;
;             PG8_LDA(At, 1, 1); PG8_STAGE(PG8_SB(1, 0), b3, voffB); PG8_STAGE(PG8_SB(1, 1), b3 + hstepB, voffB); PG8_STAGE(PG8_SA(1, 0), a3, voffA);
;             PG8_WAIT_V(8); PG8_WAIT_L(0); PG8_BAR; PG8_MMA(1, 0, At, B0); PG8_MMA(1, 1, At, B1); PG8_BAR; PG8_SCHED;
;         }
;         if constexpr (ALIGN_EPI) { if (wr == 0) PG8_BAR; }
	s_add_i32 s67, 0, 0x18000
	v_add_u32_e32 v147, s67, v1
	s_add_i32 s68, 0, 0x1c000
	ds_read_b128 v[148:151], v147
	ds_read_b128 v[152:155], v147 offset:1024
	ds_read_b128 v[156:159], v147 offset:2048
	ds_read_b128 v[160:163], v147 offset:3072
	v_add_u32_e32 v147, s68, v1
	ds_read_b128 v[164:167], v147
	ds_read_b128 v[168:171], v147 offset:1024
	ds_read_b128 v[172:175], v147 offset:2048
	ds_read_b128 v[176:179], v147 offset:3072
	s_add_u32 s38, s38, 0x100000
	s_addc_u32 s39, s39, 0
	s_mov_b32 m0, s45
	ds_read_b128 v[180:183], v146 offset:32768
	ds_read_b128 v[184:187], v146 offset:33792
	ds_read_b128 v[188:191], v146 offset:34816
	ds_read_b128 v[192:195], v146 offset:35840
	ds_read_b128 v[196:199], v146 offset:36864
	ds_read_b128 v[200:203], v146 offset:37888
	ds_read_b128 v[204:207], v146 offset:38912
	ds_read_b128 v[208:211], v146 offset:39936
	global_load_lds_dwordx4 v130, s[38:39]
	s_mov_b32 m0, s46
	s_nop 0
	global_load_lds_dwordx4 v134, s[38:39]
	s_waitcnt vmcnt(8)
	s_waitcnt lgkmcnt(0)
	s_barrier
	s_waitcnt lgkmcnt(0)
	v_mfma_f32_16x16x32_bf16 v[126:129], v[148:151], v[180:183], v[126:129]
	v_mfma_f32_16x16x32_bf16 v[122:125], v[156:159], v[180:183], v[122:125]
	v_mfma_f32_16x16x32_bf16 v[118:121], v[148:151], v[188:191], v[118:121]
	v_mfma_f32_16x16x32_bf16 v[110:113], v[156:159], v[188:191], v[110:113]
	v_mfma_f32_16x16x32_bf16 v[102:105], v[148:151], v[196:199], v[102:105]
	v_mfma_f32_16x16x32_bf16 v[94:97], v[156:159], v[196:199], v[94:97]
	v_mfma_f32_16x16x32_bf16 v[86:89], v[148:151], v[204:207], v[86:89]
	v_mfma_f32_16x16x32_bf16 v[78:81], v[156:159], v[204:207], v[78:81]
	v_mfma_f32_16x16x32_bf16 v[126:129], v[152:155], v[184:187], v[126:129]
	v_mfma_f32_16x16x32_bf16 v[122:125], v[160:163], v[184:187], v[122:125]
	v_mfma_f32_16x16x32_bf16 v[118:121], v[152:155], v[192:195], v[118:121]
	v_mfma_f32_16x16x32_bf16 v[110:113], v[160:163], v[192:195], v[110:113]
	v_mfma_f32_16x16x32_bf16 v[102:105], v[152:155], v[200:203], v[102:105]
	v_mfma_f32_16x16x32_bf16 v[94:97], v[160:163], v[200:203], v[94:97]
	v_mfma_f32_16x16x32_bf16 v[86:89], v[152:155], v[208:211], v[86:89]
	v_mfma_f32_16x16x32_bf16 v[78:81], v[160:163], v[208:211], v[78:81]
	v_mfma_f32_16x16x32_bf16 v[114:117], v[164:167], v[180:183], v[114:117]
	v_mfma_f32_16x16x32_bf16 v[106:109], v[172:175], v[180:183], v[106:109]
	v_mfma_f32_16x16x32_bf16 v[98:101], v[164:167], v[188:191], v[98:101]
	v_mfma_f32_16x16x32_bf16 v[90:93], v[172:175], v[188:191], v[90:93]
	v_mfma_f32_16x16x32_bf16 v[82:85], v[164:167], v[196:199], v[82:85]
	v_mfma_f32_16x16x32_bf16 v[74:77], v[172:175], v[196:199], v[74:77]
	v_mfma_f32_16x16x32_bf16 v[70:73], v[164:167], v[204:207], v[70:73]
	v_mfma_f32_16x16x32_bf16 v[66:69], v[172:175], v[204:207], v[66:69]
	v_mfma_f32_16x16x32_bf16 v[114:117], v[168:171], v[184:187], v[114:117]
	v_mfma_f32_16x16x32_bf16 v[106:109], v[176:179], v[184:187], v[106:109]
	v_mfma_f32_16x16x32_bf16 v[98:101], v[168:171], v[192:195], v[98:101]
	v_mfma_f32_16x16x32_bf16 v[90:93], v[176:179], v[192:195], v[90:93]
	v_mfma_f32_16x16x32_bf16 v[82:85], v[168:171], v[200:203], v[82:85]
	v_mfma_f32_16x16x32_bf16 v[74:77], v[176:179], v[200:203], v[74:77]
	v_mfma_f32_16x16x32_bf16 v[70:73], v[168:171], v[208:211], v[70:73]
	v_mfma_f32_16x16x32_bf16 v[66:69], v[176:179], v[208:211], v[66:69]
	s_barrier
	s_add_i32 s38, s67, s43
	s_mov_b32 m0, s38
	ds_read_b128 v[180:183], v146 offset:49152
	ds_read_b128 v[184:187], v146 offset:50176
	ds_read_b128 v[188:191], v146 offset:51200
	ds_read_b128 v[192:195], v146 offset:52224
	ds_read_b128 v[196:199], v146 offset:53248
	ds_read_b128 v[200:203], v146 offset:54272
	ds_read_b128 v[204:207], v146 offset:55296
	ds_read_b128 v[208:211], v146 offset:56320
	global_load_lds_dwordx4 v132, s[98:99]
	s_add_i32 m0, s38, 0x2000
	s_add_u32 s36, s36, 0x100080
	s_addc_u32 s37, s37, 0
	s_add_i32 s38, s68, s43
	global_load_lds_dwordx4 v136, s[98:99]
	s_mov_b32 m0, s38
	s_nop 0
	global_load_lds_dwordx4 v132, s[36:37]
	s_add_i32 m0, s38, 0x2000
	s_nop 0
	global_load_lds_dwordx4 v136, s[36:37]
	s_mov_b32 m0, s48
	s_nop 0
	global_load_lds_dwordx4 v130, s[100:101]
	s_mov_b32 m0, s49
	s_nop 0
	global_load_lds_dwordx4 v134, s[100:101]
	s_waitcnt vmcnt(8)
	s_waitcnt lgkmcnt(0)
	s_barrier
	s_waitcnt lgkmcnt(0)
	v_mfma_f32_16x16x32_bf16 v[62:65], v[148:151], v[180:183], v[62:65]
	v_mfma_f32_16x16x32_bf16 v[58:61], v[156:159], v[180:183], v[58:61]
	v_mfma_f32_16x16x32_bf16 v[54:57], v[148:151], v[188:191], v[54:57]
	v_mfma_f32_16x16x32_bf16 v[46:49], v[156:159], v[188:191], v[46:49]
	v_mfma_f32_16x16x32_bf16 v[38:41], v[148:151], v[196:199], v[38:41]
	v_mfma_f32_16x16x32_bf16 v[30:33], v[156:159], v[196:199], v[30:33]
	v_mfma_f32_16x16x32_bf16 v[22:25], v[148:151], v[204:207], v[22:25]
	v_mfma_f32_16x16x32_bf16 v[14:17], v[156:159], v[204:207], v[14:17]
	v_mfma_f32_16x16x32_bf16 v[62:65], v[152:155], v[184:187], v[62:65]
	v_mfma_f32_16x16x32_bf16 v[58:61], v[160:163], v[184:187], v[58:61]
	v_mfma_f32_16x16x32_bf16 v[54:57], v[152:155], v[192:195], v[54:57]
	v_mfma_f32_16x16x32_bf16 v[46:49], v[160:163], v[192:195], v[46:49]
	v_mfma_f32_16x16x32_bf16 v[38:41], v[152:155], v[200:203], v[38:41]
	v_mfma_f32_16x16x32_bf16 v[30:33], v[160:163], v[200:203], v[30:33]
	v_mfma_f32_16x16x32_bf16 v[22:25], v[152:155], v[208:211], v[22:25]
	v_mfma_f32_16x16x32_bf16 v[14:17], v[160:163], v[208:211], v[14:17]
	v_mfma_f32_16x16x32_bf16 v[50:53], v[164:167], v[180:183], v[50:53]
	v_mfma_f32_16x16x32_bf16 v[42:45], v[172:175], v[180:183], v[42:45]
	v_mfma_f32_16x16x32_bf16 v[34:37], v[164:167], v[188:191], v[34:37]
	v_mfma_f32_16x16x32_bf16 v[26:29], v[172:175], v[188:191], v[26:29]
	v_mfma_f32_16x16x32_bf16 v[18:21], v[164:167], v[196:199], v[18:21]
	v_mfma_f32_16x16x32_bf16 v[10:13], v[172:175], v[196:199], v[10:13]
	v_mfma_f32_16x16x32_bf16 v[6:9], v[164:167], v[204:207], v[6:9]
	v_mfma_f32_16x16x32_bf16 v[2:5], v[172:175], v[204:207], v[2:5]
	v_mfma_f32_16x16x32_bf16 v[50:53], v[168:171], v[184:187], v[50:53]
	v_mfma_f32_16x16x32_bf16 v[42:45], v[176:179], v[184:187], v[42:45]
	v_mfma_f32_16x16x32_bf16 v[34:37], v[168:171], v[192:195], v[34:37]
	v_mfma_f32_16x16x32_bf16 v[26:29], v[176:179], v[192:195], v[26:29]
	v_mfma_f32_16x16x32_bf16 v[18:21], v[168:171], v[200:203], v[18:21]
	v_mfma_f32_16x16x32_bf16 v[10:13], v[176:179], v[200:203], v[10:13]
	v_mfma_f32_16x16x32_bf16 v[6:9], v[168:171], v[208:211], v[6:9]
	v_mfma_f32_16x16x32_bf16 v[2:5], v[176:179], v[208:211], v[2:5]
	s_barrier
	s_add_i32 s66, s66, 2
	s_add_u32 s34, s34, 0x100
	s_addc_u32 s35, s35, 0
	s_add_u32 s64, s64, 0x100
	s_addc_u32 s65, s65, 0
	s_cmp_gt_u32 s66, 61
	s_cbranch_scc0 .LBB0_393
	s_and_b64 vcc, exec, s[10:11]
	s_cbranch_vccz .LBB0_396
	s_barrier

; #define PG8_STAGE(bufoff, gbase, voff) do { _Pragma("unroll") for (int _i = 0; _i < 2; ++_i) \
;         __builtin_amdgcn_global_load_lds((const unsigned*)((const char*)(gbase) + (voff)[_i]), (PG8_LAS unsigned*)(lds + (bufoff) + ldsw + _i * 8192), 16, 0, 0); } while (0)
; #define PG8_LDA(dst, b, h) do { _Pragma("unroll") for (int m = 0; m < 4; ++m) _Pragma("unroll") for (int k = 0; k < 2; ++k) dst[m][k] = *(const PG8_LAS bf16x8*)(lds + PG8_SA(b, h) + aoff + m * 2048 + k * 1024); } while (0)
; #define PG8_LDB(dst, b, h) do { _Pragma("unroll") for (int n = 0; n < 2; ++n) _Pragma("unroll") for (int k = 0; k < 2; ++k) dst[n][k] = *(const PG8_LAS bf16x8*)(lds + PG8_SB(b, h) + boff + n * 2048 + k * 1024); } while (0)
; #define PG8_MMA(ai, bj, At, Bt) do { __builtin_amdgcn_s_setprio(1); _Pragma("unroll") for (int m = 0; m < 4; ++m) _Pragma("unroll") for (int n = 0; n < 2; ++n) _Pragma("unroll") for (int k = 0; k < 2; ++k) \
;         acc[ai][bj][m][n] = __builtin_amdgcn_mfma_f32_16x16x32_bf16(Bt[n][k], At[m][k], acc[ai][bj][m][n], 0, 0, 0); __builtin_amdgcn_s_setprio(0); } while (0)
; #define PG8_WAIT_V(n) asm volatile("s_waitcnt vmcnt(" #n ")" ::: "memory")
; #define PG8_WAIT_L(n) asm volatile("s_waitcnt lgkmcnt(" #n ")" ::: "memory")
; #define PG8_BAR __builtin_amdgcn_s_barrier()
; #define PG8_SCHED __builtin_amdgcn_sched_barrier(0)
; template <class Epi, class Sched, bool ALIGN_EPI = false>
; __device__ __forceinline__ void gemm_phase(PG8_LAS unsigned char* lds, const Gemm g, const Sched& S, const Epi& E) {
;     ...
;             PG8_LDB(B0, 0, 0); PG8_LDB(B1, 0, 1); PG8_SCHED; PG8_LDA(At, 0, 0); PG8_STAGE(PG8_SA(1, 1), a1 + hstepA, voffA);
;             PG8_WAIT_V(8); PG8_WAIT_L(0); PG8_BAR; PG8_MMA(0, 0, At, B0); PG8_MMA(0, 1, At, B1); PG8_BAR; PG8_SCHED;
;             PG8_LDA(At, 0, 1); PG8_STAGE(PG8_SB(0, 0), b2, voffB); PG8_STAGE(PG8_SB(0, 1), b2 + hstepB, voffB); PG8_STAGE(PG8_SA(0, 0), a2, voffA);
;             PG8_WAIT_V(8); PG8_WAIT_L(0); PG8_BAR; PG8_MMA(1, 0, At, B0); PG8_MMA(1, 1, At, B1); PG8_BAR; PG8_SCHED;
.LBB0_535:
	ds_read_b128 v[146:149], v152
	ds_read_b128 v[156:159], v152 offset:1024
	ds_read_b128 v[160:163], v152 offset:2048
	ds_read_b128 v[164:167], v152 offset:3072
	ds_read_b128 v[168:171], v153
	ds_read_b128 v[172:175], v153 offset:1024
	ds_read_b128 v[176:179], v153 offset:2048
	ds_read_b128 v[180:183], v153 offset:3072
	s_add_u32 s38, s36, 0xfff80080
	s_addc_u32 s39, s37, -1
	s_cmp_eq_u32 s64, 28
	s_cselect_b32 s41, s27, s39
	s_cselect_b32 s40, s60, s38
	s_cselect_b32 s39, s25, s63
	s_cselect_b32 s38, s61, s62
	s_add_i32 m0, s35, 0xc000
	ds_read_b128 v[184:187], v154
	ds_read_b128 v[188:191], v154 offset:1024
	ds_read_b128 v[192:195], v154 offset:2048
	ds_read_b128 v[196:199], v154 offset:3072
	ds_read_b128 v[200:203], v154 offset:4096
	ds_read_b128 v[204:207], v154 offset:5120
	ds_read_b128 v[208:211], v154 offset:6144
	ds_read_b128 v[212:215], v154 offset:7168
	global_load_lds_dwordx4 v138, s[36:37]
	s_add_i32 m0, s35, 0xe000
	s_nop 0
	global_load_lds_dwordx4 v140, s[36:37]
	s_waitcnt vmcnt(8)
	s_waitcnt lgkmcnt(0)
	s_barrier
	s_waitcnt lgkmcnt(0)
	v_mfma_f32_16x16x32_bf16 v[126:129], v[146:149], v[184:187], v[126:129]
	v_mfma_f32_16x16x32_bf16 v[122:125], v[160:163], v[184:187], v[122:125]
	v_mfma_f32_16x16x32_bf16 v[110:113], v[146:149], v[192:195], v[110:113]
	v_mfma_f32_16x16x32_bf16 v[106:109], v[160:163], v[192:195], v[106:109]
	v_mfma_f32_16x16x32_bf16 v[94:97], v[146:149], v[200:203], v[94:97]
	v_mfma_f32_16x16x32_bf16 v[90:93], v[160:163], v[200:203], v[90:93]
	v_mfma_f32_16x16x32_bf16 v[78:81], v[146:149], v[208:211], v[78:81]
	v_mfma_f32_16x16x32_bf16 v[74:77], v[160:163], v[208:211], v[74:77]
	v_mfma_f32_16x16x32_bf16 v[126:129], v[156:159], v[188:191], v[126:129]
	v_mfma_f32_16x16x32_bf16 v[122:125], v[164:167], v[188:191], v[122:125]
	v_mfma_f32_16x16x32_bf16 v[110:113], v[156:159], v[196:199], v[110:113]
	v_mfma_f32_16x16x32_bf16 v[106:109], v[164:167], v[196:199], v[106:109]
	v_mfma_f32_16x16x32_bf16 v[94:97], v[156:159], v[204:207], v[94:97]
	v_mfma_f32_16x16x32_bf16 v[90:93], v[164:167], v[204:207], v[90:93]
	v_mfma_f32_16x16x32_bf16 v[78:81], v[156:159], v[212:215], v[78:81]
	v_mfma_f32_16x16x32_bf16 v[74:77], v[164:167], v[212:215], v[74:77]
	v_mfma_f32_16x16x32_bf16 v[118:121], v[168:171], v[184:187], v[118:121]
	v_mfma_f32_16x16x32_bf16 v[114:117], v[176:179], v[184:187], v[114:117]
	v_mfma_f32_16x16x32_bf16 v[102:105], v[168:171], v[192:195], v[102:105]
	v_mfma_f32_16x16x32_bf16 v[98:101], v[176:179], v[192:195], v[98:101]
	v_mfma_f32_16x16x32_bf16 v[86:89], v[168:171], v[200:203], v[86:89]
	v_mfma_f32_16x16x32_bf16 v[82:85], v[176:179], v[200:203], v[82:85]
	v_mfma_f32_16x16x32_bf16 v[70:73], v[168:171], v[208:211], v[70:73]
	v_mfma_f32_16x16x32_bf16 v[66:69], v[176:179], v[208:211], v[66:69]
	v_mfma_f32_16x16x32_bf16 v[118:121], v[172:175], v[188:191], v[118:121]
	v_mfma_f32_16x16x32_bf16 v[114:117], v[180:183], v[188:191], v[114:117]
	v_mfma_f32_16x16x32_bf16 v[102:105], v[172:175], v[196:199], v[102:105]
	v_mfma_f32_16x16x32_bf16 v[98:101], v[180:183], v[196:199], v[98:101]
	v_mfma_f32_16x16x32_bf16 v[86:89], v[172:175], v[204:207], v[86:89]
	v_mfma_f32_16x16x32_bf16 v[82:85], v[180:183], v[204:207], v[82:85]
	v_mfma_f32_16x16x32_bf16 v[70:73], v[172:175], v[212:215], v[70:73]
	v_mfma_f32_16x16x32_bf16 v[66:69], v[180:183], v[212:215], v[66:69]
	s_barrier
	s_add_i32 s65, s53, s45
	s_add_u32 s98, s38, s14
	s_addc_u32 s99, s39, s15
	s_mov_b32 m0, s65
	ds_read_b128 v[184:187], v154 offset:16384
	ds_read_b128 v[188:191], v154 offset:17408
	ds_read_b128 v[192:195], v154 offset:18432
	ds_read_b128 v[196:199], v154 offset:19456
	ds_read_b128 v[200:203], v154 offset:20480
	ds_read_b128 v[204:207], v154 offset:21504
	ds_read_b128 v[208:211], v154 offset:22528
	ds_read_b128 v[212:215], v154 offset:23552
	global_load_lds_dwordx4 v132, s[38:39]
	s_add_i32 m0, s65, 0x2000
	s_add_u32 s66, s38, 0x80000
	s_addc_u32 s67, s39, 0
	s_add_i32 s65, s54, s45
	global_load_lds_dwordx4 v136, s[38:39]
	s_mov_b32 m0, s65
	s_nop 0
	global_load_lds_dwordx4 v132, s[66:67]
	s_add_i32 m0, s65, 0x2000
	s_nop 0
	global_load_lds_dwordx4 v136, s[66:67]
	s_add_u32 s100, s40, s14
	s_addc_u32 s101, s41, s15
	s_mov_b32 m0, s35
	s_nop 0
	global_load_lds_dwordx4 v130, s[40:41]
	s_mov_b32 m0, s46
	s_nop 0
	global_load_lds_dwordx4 v134, s[40:41]
	s_waitcnt vmcnt(8)
	s_waitcnt lgkmcnt(0)
	s_barrier
	s_waitcnt lgkmcnt(0)
	v_mfma_f32_16x16x32_bf16 v[62:65], v[146:149], v[184:187], v[62:65]
	v_mfma_f32_16x16x32_bf16 v[58:61], v[160:163], v[184:187], v[58:61]
	v_mfma_f32_16x16x32_bf16 v[46:49], v[146:149], v[192:195], v[46:49]
	v_mfma_f32_16x16x32_bf16 v[42:45], v[160:163], v[192:195], v[42:45]
	v_mfma_f32_16x16x32_bf16 v[30:33], v[146:149], v[200:203], v[30:33]
	v_mfma_f32_16x16x32_bf16 v[26:29], v[160:163], v[200:203], v[26:29]
	v_mfma_f32_16x16x32_bf16 v[14:17], v[146:149], v[208:211], v[14:17]
	v_mfma_f32_16x16x32_bf16 v[10:13], v[160:163], v[208:211], v[10:13]
	v_mfma_f32_16x16x32_bf16 v[62:65], v[156:159], v[188:191], v[62:65]
	v_mfma_f32_16x16x32_bf16 v[58:61], v[164:167], v[188:191], v[58:61]
	v_mfma_f32_16x16x32_bf16 v[46:49], v[156:159], v[196:199], v[46:49]
	v_mfma_f32_16x16x32_bf16 v[42:45], v[164:167], v[196:199], v[42:45]
	v_mfma_f32_16x16x32_bf16 v[30:33], v[156:159], v[204:207], v[30:33]
	v_mfma_f32_16x16x32_bf16 v[26:29], v[164:167], v[204:207], v[26:29]
	v_mfma_f32_16x16x32_bf16 v[14:17], v[156:159], v[212:215], v[14:17]
	v_mfma_f32_16x16x32_bf16 v[10:13], v[164:167], v[212:215], v[10:13]
	v_mfma_f32_16x16x32_bf16 v[54:57], v[168:171], v[184:187], v[54:57]
	v_mfma_f32_16x16x32_bf16 v[50:53], v[176:179], v[184:187], v[50:53]
	v_mfma_f32_16x16x32_bf16 v[38:41], v[168:171], v[192:195], v[38:41]
	v_mfma_f32_16x16x32_bf16 v[34:37], v[176:179], v[192:195], v[34:37]
	v_mfma_f32_16x16x32_bf16 v[22:25], v[168:171], v[200:203], v[22:25]
	v_mfma_f32_16x16x32_bf16 v[18:21], v[176:179], v[200:203], v[18:21]
	v_mfma_f32_16x16x32_bf16 v[6:9], v[168:171], v[208:211], v[6:9]
	v_mfma_f32_16x16x32_bf16 v[2:5], v[176:179], v[208:211], v[2:5]
	v_mfma_f32_16x16x32_bf16 v[54:57], v[172:175], v[188:191], v[54:57]
	v_mfma_f32_16x16x32_bf16 v[50:53], v[180:183], v[188:191], v[50:53]
	v_mfma_f32_16x16x32_bf16 v[38:41], v[172:175], v[196:199], v[38:41]
	v_mfma_f32_16x16x32_bf16 v[34:37], v[180:183], v[196:199], v[34:37]
	v_mfma_f32_16x16x32_bf16 v[22:25], v[172:175], v[204:207], v[22:25]
	v_mfma_f32_16x16x32_bf16 v[18:21], v[180:183], v[204:207], v[18:21]
	v_mfma_f32_16x16x32_bf16 v[6:9], v[172:175], v[212:215], v[6:9]
	v_mfma_f32_16x16x32_bf16 v[2:5], v[180:183], v[212:215], v[2:5]
	s_barrier
; #define PG8_STAGE(bufoff, gbase, voff) do { _Pragma("unroll") for (int _i = 0; _i < 2; ++_i) \
;         __builtin_amdgcn_global_load_lds((const unsigned*)((const char*)(gbase) + (voff)[_i]), (PG8_LAS unsigned*)(lds + (bufoff) + ldsw + _i * 8192), 16, 0, 0); } while (0)
; #define PG8_LDA(dst, b, h) do { _Pragma("unroll") for (int m = 0; m < 4; ++m) _Pragma("unroll") for (int k = 0; k < 2; ++k) dst[m][k] = *(const PG8_LAS bf16x8*)(lds + PG8_SA(b, h) + aoff + m * 2048 + k * 1024); } while (0)
; #define PG8_LDB(dst, b, h) do { _Pragma("unroll") for (int n = 0; n < 2; ++n) _Pragma("unroll") for (int k = 0; k < 2; ++k) dst[n][k] = *(const PG8_LAS bf16x8*)(lds + PG8_SB(b, h) + boff + n * 2048 + k * 1024); } while (0)
; #define PG8_MMA(ai, bj, At, Bt) do { __builtin_amdgcn_s_setprio(1); _Pragma("unroll") for (int m = 0; m < 4; ++m) _Pragma("unroll") for (int n = 0; n < 2; ++n) _Pragma("unroll") for (int k = 0; k < 2; ++k) \
;         acc[ai][bj][m][n] = __builtin_amdgcn_mfma_f32_16x16x32_bf16(Bt[n][k], At[m][k], acc[ai][bj][m][n], 0, 0, 0); __builtin_amdgcn_s_setprio(0); } while (0)
; #define PG8_WAIT_V(n) asm volatile("s_waitcnt vmcnt(" #n ")" ::: "memory")
; #define PG8_WAIT_L(n) asm volatile("s_waitcnt lgkmcnt(" #n ")" ::: "memory")
; #define PG8_BAR __builtin_amdgcn_s_barrier()
; #define PG8_SCHED __builtin_amdgcn_sched_barrier(0)
; template <class Epi, class Sched, bool ALIGN_EPI = false>
; __device__ __forceinline__ void gemm_phase(PG8_LAS unsigned char* lds, const Gemm g, const Sched& S, const Epi& E) {
;     ...
;             PG8_LDB(B0, 1, 0); PG8_LDB(B1, 1, 1); PG8_SCHED; PG8_LDA(At, 1, 0); PG8_STAGE(PG8_SA(0, 1), a2 + hstepA, voffA);
;             PG8_WAIT_V(8); PG8_WAIT_L(0); PG8_BAR; PG8_MMA(0, 0, At, B0); PG8_MMA(0, 1, At, B1); PG8_BAR; PG8_SCHED;
;             PG8_LDA(At, 1, 1); PG8_STAGE(PG8_SB(1, 0), b3, voffB); PG8_STAGE(PG8_SB(1, 1), b3 + hstepB, voffB); PG8_STAGE(PG8_SA(1, 0), a3, voffA);
;             PG8_WAIT_V(8); PG8_WAIT_L(0); PG8_BAR; PG8_MMA(1, 0, At, B0); PG8_MMA(1, 1, At, B1); PG8_BAR; PG8_SCHED;
;         }
;         if constexpr (ALIGN_EPI) { if (wr == 0) PG8_BAR; }
	s_add_i32 s65, 0, 0x18000
	v_add_u32_e32 v155, s65, v1
	s_add_i32 s66, 0, 0x1c000
	ds_read_b128 v[146:149], v155
	ds_read_b128 v[156:159], v155 offset:1024
	ds_read_b128 v[160:163], v155 offset:2048
	ds_read_b128 v[164:167], v155 offset:3072
	v_add_u32_e32 v155, s66, v1
	ds_read_b128 v[168:171], v155
	ds_read_b128 v[172:175], v155 offset:1024
	ds_read_b128 v[176:179], v155 offset:2048
	ds_read_b128 v[180:183], v155 offset:3072
	s_add_u32 s40, s40, 0x80000
	s_addc_u32 s41, s41, 0
	s_mov_b32 m0, s47
	ds_read_b128 v[184:187], v154 offset:32768
	ds_read_b128 v[188:191], v154 offset:33792
	ds_read_b128 v[192:195], v154 offset:34816
	ds_read_b128 v[196:199], v154 offset:35840
	ds_read_b128 v[200:203], v154 offset:36864
	ds_read_b128 v[204:207], v154 offset:37888
	ds_read_b128 v[208:211], v154 offset:38912
	ds_read_b128 v[212:215], v154 offset:39936
	global_load_lds_dwordx4 v130, s[40:41]
	s_mov_b32 m0, s48
	s_nop 0
	global_load_lds_dwordx4 v134, s[40:41]
	s_waitcnt vmcnt(8)
	s_waitcnt lgkmcnt(0)
	s_barrier
	s_waitcnt lgkmcnt(0)
	v_mfma_f32_16x16x32_bf16 v[126:129], v[146:149], v[184:187], v[126:129]
	v_mfma_f32_16x16x32_bf16 v[122:125], v[160:163], v[184:187], v[122:125]
	v_mfma_f32_16x16x32_bf16 v[110:113], v[146:149], v[192:195], v[110:113]
	v_mfma_f32_16x16x32_bf16 v[106:109], v[160:163], v[192:195], v[106:109]
	v_mfma_f32_16x16x32_bf16 v[94:97], v[146:149], v[200:203], v[94:97]
	v_mfma_f32_16x16x32_bf16 v[90:93], v[160:163], v[200:203], v[90:93]
	v_mfma_f32_16x16x32_bf16 v[78:81], v[146:149], v[208:211], v[78:81]
	v_mfma_f32_16x16x32_bf16 v[74:77], v[160:163], v[208:211], v[74:77]
	v_mfma_f32_16x16x32_bf16 v[126:129], v[156:159], v[188:191], v[126:129]
	v_mfma_f32_16x16x32_bf16 v[122:125], v[164:167], v[188:191], v[122:125]
	v_mfma_f32_16x16x32_bf16 v[110:113], v[156:159], v[196:199], v[110:113]
	v_mfma_f32_16x16x32_bf16 v[106:109], v[164:167], v[196:199], v[106:109]
	v_mfma_f32_16x16x32_bf16 v[94:97], v[156:159], v[204:207], v[94:97]
	v_mfma_f32_16x16x32_bf16 v[90:93], v[164:167], v[204:207], v[90:93]
	v_mfma_f32_16x16x32_bf16 v[78:81], v[156:159], v[212:215], v[78:81]
	v_mfma_f32_16x16x32_bf16 v[74:77], v[164:167], v[212:215], v[74:77]
	v_mfma_f32_16x16x32_bf16 v[118:121], v[168:171], v[184:187], v[118:121]
	v_mfma_f32_16x16x32_bf16 v[114:117], v[176:179], v[184:187], v[114:117]
	v_mfma_f32_16x16x32_bf16 v[102:105], v[168:171], v[192:195], v[102:105]
	v_mfma_f32_16x16x32_bf16 v[98:101], v[176:179], v[192:195], v[98:101]
	v_mfma_f32_16x16x32_bf16 v[86:89], v[168:171], v[200:203], v[86:89]
	v_mfma_f32_16x16x32_bf16 v[82:85], v[176:179], v[200:203], v[82:85]
	v_mfma_f32_16x16x32_bf16 v[70:73], v[168:171], v[208:211], v[70:73]
	v_mfma_f32_16x16x32_bf16 v[66:69], v[176:179], v[208:211], v[66:69]
	v_mfma_f32_16x16x32_bf16 v[118:121], v[172:175], v[188:191], v[118:121]
	v_mfma_f32_16x16x32_bf16 v[114:117], v[180:183], v[188:191], v[114:117]
	v_mfma_f32_16x16x32_bf16 v[102:105], v[172:175], v[196:199], v[102:105]
	v_mfma_f32_16x16x32_bf16 v[98:101], v[180:183], v[196:199], v[98:101]
	v_mfma_f32_16x16x32_bf16 v[86:89], v[172:175], v[204:207], v[86:89]
	v_mfma_f32_16x16x32_bf16 v[82:85], v[180:183], v[204:207], v[82:85]
	v_mfma_f32_16x16x32_bf16 v[70:73], v[172:175], v[212:215], v[70:73]
	v_mfma_f32_16x16x32_bf16 v[66:69], v[180:183], v[212:215], v[66:69]
	s_barrier
	s_add_i32 s40, s65, s45
	s_mov_b32 m0, s40
	ds_read_b128 v[184:187], v154 offset:49152
	ds_read_b128 v[188:191], v154 offset:50176
	ds_read_b128 v[192:195], v154 offset:51200
	ds_read_b128 v[196:199], v154 offset:52224
	ds_read_b128 v[200:203], v154 offset:53248
	ds_read_b128 v[204:207], v154 offset:54272
	ds_read_b128 v[208:211], v154 offset:55296
	ds_read_b128 v[212:215], v154 offset:56320
	global_load_lds_dwordx4 v132, s[98:99]
	s_add_i32 m0, s40, 0x2000
	s_add_u32 s38, s38, 0x80080
	s_addc_u32 s39, s39, 0
	s_add_i32 s40, s66, s45
	global_load_lds_dwordx4 v136, s[98:99]
	s_mov_b32 m0, s40
	s_nop 0
	global_load_lds_dwordx4 v132, s[38:39]
	s_add_i32 m0, s40, 0x2000
	s_nop 0
	global_load_lds_dwordx4 v136, s[38:39]
	s_mov_b32 m0, s50
	s_nop 0
	global_load_lds_dwordx4 v130, s[100:101]
	s_mov_b32 m0, s51
	s_nop 0
	global_load_lds_dwordx4 v134, s[100:101]
	s_waitcnt vmcnt(8)
	s_waitcnt lgkmcnt(0)
	s_barrier
	s_waitcnt lgkmcnt(0)
	v_mfma_f32_16x16x32_bf16 v[62:65], v[146:149], v[184:187], v[62:65]
	v_mfma_f32_16x16x32_bf16 v[58:61], v[160:163], v[184:187], v[58:61]
	v_mfma_f32_16x16x32_bf16 v[46:49], v[146:149], v[192:195], v[46:49]
	v_mfma_f32_16x16x32_bf16 v[42:45], v[160:163], v[192:195], v[42:45]
	v_mfma_f32_16x16x32_bf16 v[30:33], v[146:149], v[200:203], v[30:33]
	v_mfma_f32_16x16x32_bf16 v[26:29], v[160:163], v[200:203], v[26:29]
	v_mfma_f32_16x16x32_bf16 v[14:17], v[146:149], v[208:211], v[14:17]
	v_mfma_f32_16x16x32_bf16 v[10:13], v[160:163], v[208:211], v[10:13]
	v_mfma_f32_16x16x32_bf16 v[62:65], v[156:159], v[188:191], v[62:65]
	v_mfma_f32_16x16x32_bf16 v[58:61], v[164:167], v[188:191], v[58:61]
	v_mfma_f32_16x16x32_bf16 v[46:49], v[156:159], v[196:199], v[46:49]
	v_mfma_f32_16x16x32_bf16 v[42:45], v[164:167], v[196:199], v[42:45]
	v_mfma_f32_16x16x32_bf16 v[30:33], v[156:159], v[204:207], v[30:33]
	v_mfma_f32_16x16x32_bf16 v[26:29], v[164:167], v[204:207], v[26:29]
	v_mfma_f32_16x16x32_bf16 v[14:17], v[156:159], v[212:215], v[14:17]
	v_mfma_f32_16x16x32_bf16 v[10:13], v[164:167], v[212:215], v[10:13]
	v_mfma_f32_16x16x32_bf16 v[54:57], v[168:171], v[184:187], v[54:57]
	v_mfma_f32_16x16x32_bf16 v[50:53], v[176:179], v[184:187], v[50:53]
	v_mfma_f32_16x16x32_bf16 v[38:41], v[168:171], v[192:195], v[38:41]
	v_mfma_f32_16x16x32_bf16 v[34:37], v[176:179], v[192:195], v[34:37]
	v_mfma_f32_16x16x32_bf16 v[22:25], v[168:171], v[200:203], v[22:25]
	v_mfma_f32_16x16x32_bf16 v[18:21], v[176:179], v[200:203], v[18:21]
	v_mfma_f32_16x16x32_bf16 v[6:9], v[168:171], v[208:211], v[6:9]
	v_mfma_f32_16x16x32_bf16 v[2:5], v[176:179], v[208:211], v[2:5]
	v_mfma_f32_16x16x32_bf16 v[54:57], v[172:175], v[188:191], v[54:57]
	v_mfma_f32_16x16x32_bf16 v[50:53], v[180:183], v[188:191], v[50:53]
	v_mfma_f32_16x16x32_bf16 v[38:41], v[172:175], v[196:199], v[38:41]
	v_mfma_f32_16x16x32_bf16 v[34:37], v[180:183], v[196:199], v[34:37]
	v_mfma_f32_16x16x32_bf16 v[22:25], v[172:175], v[204:207], v[22:25]
	v_mfma_f32_16x16x32_bf16 v[18:21], v[180:183], v[204:207], v[18:21]
	v_mfma_f32_16x16x32_bf16 v[6:9], v[172:175], v[212:215], v[6:9]
	v_mfma_f32_16x16x32_bf16 v[2:5], v[180:183], v[212:215], v[2:5]
	s_barrier
	s_add_i32 s64, s64, 2
	s_add_u32 s36, s36, 0x100
	s_addc_u32 s37, s37, 0
	s_add_u32 s62, s62, 0x100
	s_addc_u32 s63, s63, 0
	s_cmp_gt_u32 s64, 29
	s_cbranch_scc0 .LBB0_535
	s_and_b64 vcc, exec, s[16:17]
	s_cbranch_vccz .LBB0_538
	s_barrier

; #define PG8_STAGE(bufoff, gbase, voff) do { _Pragma("unroll") for (int _i = 0; _i < 2; ++_i) \
;         __builtin_amdgcn_global_load_lds((const unsigned*)((const char*)(gbase) + (voff)[_i]), (PG8_LAS unsigned*)(lds + (bufoff) + ldsw + _i * 8192), 16, 0, 0); } while (0)
; #define PG8_LDA(dst, b, h) do { _Pragma("unroll") for (int m = 0; m < 4; ++m) _Pragma("unroll") for (int k = 0; k < 2; ++k) dst[m][k] = *(const PG8_LAS bf16x8*)(lds + PG8_SA(b, h) + aoff + m * 2048 + k * 1024); } while (0)
; #define PG8_LDB(dst, b, h) do { _Pragma("unroll") for (int n = 0; n < 2; ++n) _Pragma("unroll") for (int k = 0; k < 2; ++k) dst[n][k] = *(const PG8_LAS bf16x8*)(lds + PG8_SB(b, h) + boff + n * 2048 + k * 1024); } while (0)
; #define PG8_MMA(ai, bj, At, Bt) do { __builtin_amdgcn_s_setprio(1); _Pragma("unroll") for (int m = 0; m < 4; ++m) _Pragma("unroll") for (int n = 0; n < 2; ++n) _Pragma("unroll") for (int k = 0; k < 2; ++k) \
;         acc[ai][bj][m][n] = __builtin_amdgcn_mfma_f32_16x16x32_bf16(Bt[n][k], At[m][k], acc[ai][bj][m][n], 0, 0, 0); __builtin_amdgcn_s_setprio(0); } while (0)
; #define PG8_WAIT_V(n) asm volatile("s_waitcnt vmcnt(" #n ")" ::: "memory")
; #define PG8_WAIT_L(n) asm volatile("s_waitcnt lgkmcnt(" #n ")" ::: "memory")
; #define PG8_BAR __builtin_amdgcn_s_barrier()
; #define PG8_SCHED __builtin_amdgcn_sched_barrier(0)
; template <class Epi, class Sched, bool ALIGN_EPI = false>
; __device__ __forceinline__ void gemm_phase(PG8_LAS unsigned char* lds, const Gemm g, const Sched& S, const Epi& E) {
;     ...
;             PG8_LDB(B0, 0, 0); PG8_LDB(B1, 0, 1); PG8_SCHED; PG8_LDA(At, 0, 0); PG8_STAGE(PG8_SA(1, 1), a1 + hstepA, voffA);
;             PG8_WAIT_V(8); PG8_WAIT_L(0); PG8_BAR; PG8_MMA(0, 0, At, B0); PG8_MMA(0, 1, At, B1); PG8_BAR; PG8_SCHED;
;             PG8_LDA(At, 0, 1); PG8_STAGE(PG8_SB(0, 0), b2, voffB); PG8_STAGE(PG8_SB(0, 1), b2 + hstepB, voffB); PG8_STAGE(PG8_SA(0, 0), a2, voffA);
;             PG8_WAIT_V(8); PG8_WAIT_L(0); PG8_BAR; PG8_MMA(1, 0, At, B0); PG8_MMA(1, 1, At, B1); PG8_BAR; PG8_SCHED;
.LBB0_812:
	ds_read_b128 v[146:149], v152
	ds_read_b128 v[156:159], v152 offset:1024
	ds_read_b128 v[160:163], v152 offset:2048
	ds_read_b128 v[164:167], v152 offset:3072
	ds_read_b128 v[168:171], v153
	ds_read_b128 v[172:175], v153 offset:1024
	ds_read_b128 v[176:179], v153 offset:2048
	ds_read_b128 v[180:183], v153 offset:3072
	s_add_u32 s28, s26, 0x100
	s_addc_u32 s29, s27, 0
	s_cmpk_eq_i32 s64, 0xdc
	s_cselect_b32 s35, s5, s29
	s_cselect_b32 s34, s4, s28
	s_cselect_b32 s31, s25, s63
	s_cselect_b32 s30, s24, s62
	s_add_i32 m0, s40, 0xc000
	ds_read_b128 v[184:187], v154
	ds_read_b128 v[188:191], v154 offset:1024
	ds_read_b128 v[192:195], v154 offset:2048
	ds_read_b128 v[196:199], v154 offset:3072
	ds_read_b128 v[200:203], v154 offset:4096
	ds_read_b128 v[204:207], v154 offset:5120
	ds_read_b128 v[208:211], v154 offset:6144
	ds_read_b128 v[212:215], v154 offset:7168
	global_load_lds_dwordx4 v138, s[26:27]
	s_add_i32 m0, s40, 0xe000
	s_nop 0
	global_load_lds_dwordx4 v140, s[26:27]
	s_waitcnt vmcnt(8)
	s_waitcnt lgkmcnt(0)
	s_barrier
	s_waitcnt lgkmcnt(0)
	v_mfma_f32_16x16x32_bf16 v[126:129], v[146:149], v[184:187], v[126:129]
	v_mfma_f32_16x16x32_bf16 v[122:125], v[160:163], v[184:187], v[122:125]
	v_mfma_f32_16x16x32_bf16 v[114:117], v[146:149], v[192:195], v[114:117]
	v_mfma_f32_16x16x32_bf16 v[106:109], v[160:163], v[192:195], v[106:109]
	v_mfma_f32_16x16x32_bf16 v[98:101], v[146:149], v[200:203], v[98:101]
	v_mfma_f32_16x16x32_bf16 v[90:93], v[160:163], v[200:203], v[90:93]
	v_mfma_f32_16x16x32_bf16 v[82:85], v[146:149], v[208:211], v[82:85]
	v_mfma_f32_16x16x32_bf16 v[74:77], v[160:163], v[208:211], v[74:77]
	v_mfma_f32_16x16x32_bf16 v[126:129], v[156:159], v[188:191], v[126:129]
	v_mfma_f32_16x16x32_bf16 v[122:125], v[164:167], v[188:191], v[122:125]
	v_mfma_f32_16x16x32_bf16 v[114:117], v[156:159], v[196:199], v[114:117]
	v_mfma_f32_16x16x32_bf16 v[106:109], v[164:167], v[196:199], v[106:109]
	v_mfma_f32_16x16x32_bf16 v[98:101], v[156:159], v[204:207], v[98:101]
	v_mfma_f32_16x16x32_bf16 v[90:93], v[164:167], v[204:207], v[90:93]
	v_mfma_f32_16x16x32_bf16 v[82:85], v[156:159], v[212:215], v[82:85]
	v_mfma_f32_16x16x32_bf16 v[74:77], v[164:167], v[212:215], v[74:77]
	v_mfma_f32_16x16x32_bf16 v[118:121], v[168:171], v[184:187], v[118:121]
	v_mfma_f32_16x16x32_bf16 v[110:113], v[176:179], v[184:187], v[110:113]
	v_mfma_f32_16x16x32_bf16 v[102:105], v[168:171], v[192:195], v[102:105]
	v_mfma_f32_16x16x32_bf16 v[94:97], v[176:179], v[192:195], v[94:97]
	v_mfma_f32_16x16x32_bf16 v[86:89], v[168:171], v[200:203], v[86:89]
	v_mfma_f32_16x16x32_bf16 v[78:81], v[176:179], v[200:203], v[78:81]
	v_mfma_f32_16x16x32_bf16 v[70:73], v[168:171], v[208:211], v[70:73]
	v_mfma_f32_16x16x32_bf16 v[66:69], v[176:179], v[208:211], v[66:69]
	v_mfma_f32_16x16x32_bf16 v[118:121], v[172:175], v[188:191], v[118:121]
	v_mfma_f32_16x16x32_bf16 v[110:113], v[180:183], v[188:191], v[110:113]
	v_mfma_f32_16x16x32_bf16 v[102:105], v[172:175], v[196:199], v[102:105]
	v_mfma_f32_16x16x32_bf16 v[94:97], v[180:183], v[196:199], v[94:97]
	v_mfma_f32_16x16x32_bf16 v[86:89], v[172:175], v[204:207], v[86:89]
	v_mfma_f32_16x16x32_bf16 v[78:81], v[180:183], v[204:207], v[78:81]
	v_mfma_f32_16x16x32_bf16 v[70:73], v[172:175], v[212:215], v[70:73]
	v_mfma_f32_16x16x32_bf16 v[66:69], v[180:183], v[212:215], v[66:69]
	s_barrier
	s_add_i32 s26, s48, s39
	s_add_u32 s98, s30, s12
	s_addc_u32 s99, s31, s13
	s_mov_b32 m0, s26
	ds_read_b128 v[184:187], v154 offset:16384
	ds_read_b128 v[188:191], v154 offset:17408
	ds_read_b128 v[192:195], v154 offset:18432
	ds_read_b128 v[196:199], v154 offset:19456
	ds_read_b128 v[200:203], v154 offset:20480
	ds_read_b128 v[204:207], v154 offset:21504
	ds_read_b128 v[208:211], v154 offset:22528
	ds_read_b128 v[212:215], v154 offset:23552
	global_load_lds_dwordx4 v132, s[30:31]
	s_add_i32 m0, s26, 0x2000
	s_add_u32 s26, s30, 0x380000
	s_addc_u32 s27, s31, 0
	s_add_i32 s65, s49, s39
	global_load_lds_dwordx4 v136, s[30:31]
	s_mov_b32 m0, s65
	s_nop 0
	global_load_lds_dwordx4 v132, s[26:27]
	s_add_i32 m0, s65, 0x2000
	s_nop 0
	global_load_lds_dwordx4 v136, s[26:27]
	s_add_u32 s100, s34, s12
	s_addc_u32 s101, s35, s13
	s_mov_b32 m0, s40
	s_nop 0
	global_load_lds_dwordx4 v130, s[34:35]
	s_mov_b32 m0, s41
	s_nop 0
	global_load_lds_dwordx4 v134, s[34:35]
	s_waitcnt vmcnt(8)
	s_waitcnt lgkmcnt(0)
	s_barrier
	s_waitcnt lgkmcnt(0)
	v_mfma_f32_16x16x32_bf16 v[62:65], v[146:149], v[184:187], v[62:65]
	v_mfma_f32_16x16x32_bf16 v[58:61], v[160:163], v[184:187], v[58:61]
	v_mfma_f32_16x16x32_bf16 v[50:53], v[146:149], v[192:195], v[50:53]
	v_mfma_f32_16x16x32_bf16 v[42:45], v[160:163], v[192:195], v[42:45]
	v_mfma_f32_16x16x32_bf16 v[34:37], v[146:149], v[200:203], v[34:37]
	v_mfma_f32_16x16x32_bf16 v[26:29], v[160:163], v[200:203], v[26:29]
	v_mfma_f32_16x16x32_bf16 v[18:21], v[146:149], v[208:211], v[18:21]
	v_mfma_f32_16x16x32_bf16 v[10:13], v[160:163], v[208:211], v[10:13]
	v_mfma_f32_16x16x32_bf16 v[62:65], v[156:159], v[188:191], v[62:65]
	v_mfma_f32_16x16x32_bf16 v[58:61], v[164:167], v[188:191], v[58:61]
	v_mfma_f32_16x16x32_bf16 v[50:53], v[156:159], v[196:199], v[50:53]
	v_mfma_f32_16x16x32_bf16 v[42:45], v[164:167], v[196:199], v[42:45]
	v_mfma_f32_16x16x32_bf16 v[34:37], v[156:159], v[204:207], v[34:37]
	v_mfma_f32_16x16x32_bf16 v[26:29], v[164:167], v[204:207], v[26:29]
	v_mfma_f32_16x16x32_bf16 v[18:21], v[156:159], v[212:215], v[18:21]
	v_mfma_f32_16x16x32_bf16 v[10:13], v[164:167], v[212:215], v[10:13]
	v_mfma_f32_16x16x32_bf16 v[54:57], v[168:171], v[184:187], v[54:57]
	v_mfma_f32_16x16x32_bf16 v[46:49], v[176:179], v[184:187], v[46:49]
	v_mfma_f32_16x16x32_bf16 v[38:41], v[168:171], v[192:195], v[38:41]
	v_mfma_f32_16x16x32_bf16 v[30:33], v[176:179], v[192:195], v[30:33]
	v_mfma_f32_16x16x32_bf16 v[22:25], v[168:171], v[200:203], v[22:25]
	v_mfma_f32_16x16x32_bf16 v[14:17], v[176:179], v[200:203], v[14:17]
	v_mfma_f32_16x16x32_bf16 v[6:9], v[168:171], v[208:211], v[6:9]
	v_mfma_f32_16x16x32_bf16 v[2:5], v[176:179], v[208:211], v[2:5]
	v_mfma_f32_16x16x32_bf16 v[54:57], v[172:175], v[188:191], v[54:57]
	v_mfma_f32_16x16x32_bf16 v[46:49], v[180:183], v[188:191], v[46:49]
	v_mfma_f32_16x16x32_bf16 v[38:41], v[172:175], v[196:199], v[38:41]
	v_mfma_f32_16x16x32_bf16 v[30:33], v[180:183], v[196:199], v[30:33]
	v_mfma_f32_16x16x32_bf16 v[22:25], v[172:175], v[204:207], v[22:25]
	v_mfma_f32_16x16x32_bf16 v[14:17], v[180:183], v[204:207], v[14:17]
	v_mfma_f32_16x16x32_bf16 v[6:9], v[172:175], v[212:215], v[6:9]
	v_mfma_f32_16x16x32_bf16 v[2:5], v[180:183], v[212:215], v[2:5]
	s_barrier
; #define PG8_STAGE(bufoff, gbase, voff) do { _Pragma("unroll") for (int _i = 0; _i < 2; ++_i) \
;         __builtin_amdgcn_global_load_lds((const unsigned*)((const char*)(gbase) + (voff)[_i]), (PG8_LAS unsigned*)(lds + (bufoff) + ldsw + _i * 8192), 16, 0, 0); } while (0)
; #define PG8_LDA(dst, b, h) do { _Pragma("unroll") for (int m = 0; m < 4; ++m) _Pragma("unroll") for (int k = 0; k < 2; ++k) dst[m][k] = *(const PG8_LAS bf16x8*)(lds + PG8_SA(b, h) + aoff + m * 2048 + k * 1024); } while (0)
; #define PG8_LDB(dst, b, h) do { _Pragma("unroll") for (int n = 0; n < 2; ++n) _Pragma("unroll") for (int k = 0; k < 2; ++k) dst[n][k] = *(const PG8_LAS bf16x8*)(lds + PG8_SB(b, h) + boff + n * 2048 + k * 1024); } while (0)
; #define PG8_MMA(ai, bj, At, Bt) do { __builtin_amdgcn_s_setprio(1); _Pragma("unroll") for (int m = 0; m < 4; ++m) _Pragma("unroll") for (int n = 0; n < 2; ++n) _Pragma("unroll") for (int k = 0; k < 2; ++k) \
;         acc[ai][bj][m][n] = __builtin_amdgcn_mfma_f32_16x16x32_bf16(Bt[n][k], At[m][k], acc[ai][bj][m][n], 0, 0, 0); __builtin_amdgcn_s_setprio(0); } while (0)
; #define PG8_WAIT_V(n) asm volatile("s_waitcnt vmcnt(" #n ")" ::: "memory")
; #define PG8_WAIT_L(n) asm volatile("s_waitcnt lgkmcnt(" #n ")" ::: "memory")
; #define PG8_BAR __builtin_amdgcn_s_barrier()
; #define PG8_SCHED __builtin_amdgcn_sched_barrier(0)
; template <class Epi, class Sched, bool ALIGN_EPI = false>
; __device__ __forceinline__ void gemm_phase(PG8_LAS unsigned char* lds, const Gemm g, const Sched& S, const Epi& E) {
;     ...
;             PG8_LDB(B0, 1, 0); PG8_LDB(B1, 1, 1); PG8_SCHED; PG8_LDA(At, 1, 0); PG8_STAGE(PG8_SA(0, 1), a2 + hstepA, voffA);
;             PG8_WAIT_V(8); PG8_WAIT_L(0); PG8_BAR; PG8_MMA(0, 0, At, B0); PG8_MMA(0, 1, At, B1); PG8_BAR; PG8_SCHED;
;             PG8_LDA(At, 1, 1); PG8_STAGE(PG8_SB(1, 0), b3, voffB); PG8_STAGE(PG8_SB(1, 1), b3 + hstepB, voffB); PG8_STAGE(PG8_SA(1, 0), a3, voffA);
;             PG8_WAIT_V(8); PG8_WAIT_L(0); PG8_BAR; PG8_MMA(1, 0, At, B0); PG8_MMA(1, 1, At, B1); PG8_BAR; PG8_SCHED;
;         }
;         if constexpr (ALIGN_EPI) { if (wr == 0) PG8_BAR; }
	s_add_i32 s65, 0, 0x18000
	v_add_u32_e32 v155, s65, v1
	s_add_i32 s66, 0, 0x1c000
	ds_read_b128 v[146:149], v155
	ds_read_b128 v[156:159], v155 offset:1024
	ds_read_b128 v[160:163], v155 offset:2048
	ds_read_b128 v[164:167], v155 offset:3072
	v_add_u32_e32 v155, s66, v1
	ds_read_b128 v[168:171], v155
	ds_read_b128 v[172:175], v155 offset:1024
	ds_read_b128 v[176:179], v155 offset:2048
	ds_read_b128 v[180:183], v155 offset:3072
	s_add_u32 s26, s34, 0x380000
	s_addc_u32 s27, s35, 0
	s_mov_b32 m0, s42
	ds_read_b128 v[184:187], v154 offset:32768
	ds_read_b128 v[188:191], v154 offset:33792
	ds_read_b128 v[192:195], v154 offset:34816
	ds_read_b128 v[196:199], v154 offset:35840
	ds_read_b128 v[200:203], v154 offset:36864
	ds_read_b128 v[204:207], v154 offset:37888
	ds_read_b128 v[208:211], v154 offset:38912
	ds_read_b128 v[212:215], v154 offset:39936
	global_load_lds_dwordx4 v130, s[26:27]
	s_mov_b32 m0, s43
	s_nop 0
	global_load_lds_dwordx4 v134, s[26:27]
	s_waitcnt vmcnt(8)
	s_waitcnt lgkmcnt(0)
	s_barrier
	s_waitcnt lgkmcnt(0)
	v_mfma_f32_16x16x32_bf16 v[126:129], v[146:149], v[184:187], v[126:129]
	v_mfma_f32_16x16x32_bf16 v[122:125], v[160:163], v[184:187], v[122:125]
	v_mfma_f32_16x16x32_bf16 v[114:117], v[146:149], v[192:195], v[114:117]
	v_mfma_f32_16x16x32_bf16 v[106:109], v[160:163], v[192:195], v[106:109]
	v_mfma_f32_16x16x32_bf16 v[98:101], v[146:149], v[200:203], v[98:101]
	v_mfma_f32_16x16x32_bf16 v[90:93], v[160:163], v[200:203], v[90:93]
	v_mfma_f32_16x16x32_bf16 v[82:85], v[146:149], v[208:211], v[82:85]
	v_mfma_f32_16x16x32_bf16 v[74:77], v[160:163], v[208:211], v[74:77]
	v_mfma_f32_16x16x32_bf16 v[126:129], v[156:159], v[188:191], v[126:129]
	v_mfma_f32_16x16x32_bf16 v[122:125], v[164:167], v[188:191], v[122:125]
	v_mfma_f32_16x16x32_bf16 v[114:117], v[156:159], v[196:199], v[114:117]
	v_mfma_f32_16x16x32_bf16 v[106:109], v[164:167], v[196:199], v[106:109]
	v_mfma_f32_16x16x32_bf16 v[98:101], v[156:159], v[204:207], v[98:101]
	v_mfma_f32_16x16x32_bf16 v[90:93], v[164:167], v[204:207], v[90:93]
	v_mfma_f32_16x16x32_bf16 v[82:85], v[156:159], v[212:215], v[82:85]
	v_mfma_f32_16x16x32_bf16 v[74:77], v[164:167], v[212:215], v[74:77]
	v_mfma_f32_16x16x32_bf16 v[118:121], v[168:171], v[184:187], v[118:121]
	v_mfma_f32_16x16x32_bf16 v[110:113], v[176:179], v[184:187], v[110:113]
	v_mfma_f32_16x16x32_bf16 v[102:105], v[168:171], v[192:195], v[102:105]
	v_mfma_f32_16x16x32_bf16 v[94:97], v[176:179], v[192:195], v[94:97]
	v_mfma_f32_16x16x32_bf16 v[86:89], v[168:171], v[200:203], v[86:89]
	v_mfma_f32_16x16x32_bf16 v[78:81], v[176:179], v[200:203], v[78:81]
	v_mfma_f32_16x16x32_bf16 v[70:73], v[168:171], v[208:211], v[70:73]
	v_mfma_f32_16x16x32_bf16 v[66:69], v[176:179], v[208:211], v[66:69]
	v_mfma_f32_16x16x32_bf16 v[118:121], v[172:175], v[188:191], v[118:121]
	v_mfma_f32_16x16x32_bf16 v[110:113], v[180:183], v[188:191], v[110:113]
	v_mfma_f32_16x16x32_bf16 v[102:105], v[172:175], v[196:199], v[102:105]
	v_mfma_f32_16x16x32_bf16 v[94:97], v[180:183], v[196:199], v[94:97]
	v_mfma_f32_16x16x32_bf16 v[86:89], v[172:175], v[204:207], v[86:89]
	v_mfma_f32_16x16x32_bf16 v[78:81], v[180:183], v[204:207], v[78:81]
	v_mfma_f32_16x16x32_bf16 v[70:73], v[172:175], v[212:215], v[70:73]
	v_mfma_f32_16x16x32_bf16 v[66:69], v[180:183], v[212:215], v[66:69]
	s_barrier
	s_add_i32 s26, s65, s39
	s_mov_b32 m0, s26
	ds_read_b128 v[184:187], v154 offset:49152
	ds_read_b128 v[188:191], v154 offset:50176
	ds_read_b128 v[192:195], v154 offset:51200
	ds_read_b128 v[196:199], v154 offset:52224
	ds_read_b128 v[200:203], v154 offset:53248
	ds_read_b128 v[204:207], v154 offset:54272
	ds_read_b128 v[208:211], v154 offset:55296
	ds_read_b128 v[212:215], v154 offset:56320
	global_load_lds_dwordx4 v132, s[98:99]
	s_add_i32 m0, s26, 0x2000
	s_add_u32 s26, s30, 0x380080
	s_addc_u32 s27, s31, 0
	s_add_i32 s30, s66, s39
	global_load_lds_dwordx4 v136, s[98:99]
	s_mov_b32 m0, s30
	s_nop 0
	global_load_lds_dwordx4 v132, s[26:27]
	s_add_i32 m0, s30, 0x2000
	s_nop 0
	global_load_lds_dwordx4 v136, s[26:27]
	s_mov_b32 m0, s45
	s_nop 0
	global_load_lds_dwordx4 v130, s[100:101]
	s_mov_b32 m0, s46
	s_nop 0
	global_load_lds_dwordx4 v134, s[100:101]
	s_waitcnt vmcnt(8)
	s_waitcnt lgkmcnt(0)
	s_barrier
	s_waitcnt lgkmcnt(0)
	v_mfma_f32_16x16x32_bf16 v[62:65], v[146:149], v[184:187], v[62:65]
	v_mfma_f32_16x16x32_bf16 v[58:61], v[160:163], v[184:187], v[58:61]
	v_mfma_f32_16x16x32_bf16 v[50:53], v[146:149], v[192:195], v[50:53]
	v_mfma_f32_16x16x32_bf16 v[42:45], v[160:163], v[192:195], v[42:45]
	v_mfma_f32_16x16x32_bf16 v[34:37], v[146:149], v[200:203], v[34:37]
	v_mfma_f32_16x16x32_bf16 v[26:29], v[160:163], v[200:203], v[26:29]
	v_mfma_f32_16x16x32_bf16 v[18:21], v[146:149], v[208:211], v[18:21]
	v_mfma_f32_16x16x32_bf16 v[10:13], v[160:163], v[208:211], v[10:13]
	v_mfma_f32_16x16x32_bf16 v[62:65], v[156:159], v[188:191], v[62:65]
	v_mfma_f32_16x16x32_bf16 v[58:61], v[164:167], v[188:191], v[58:61]
	v_mfma_f32_16x16x32_bf16 v[50:53], v[156:159], v[196:199], v[50:53]
	v_mfma_f32_16x16x32_bf16 v[42:45], v[164:167], v[196:199], v[42:45]
	v_mfma_f32_16x16x32_bf16 v[34:37], v[156:159], v[204:207], v[34:37]
	v_mfma_f32_16x16x32_bf16 v[26:29], v[164:167], v[204:207], v[26:29]
	v_mfma_f32_16x16x32_bf16 v[18:21], v[156:159], v[212:215], v[18:21]
	v_mfma_f32_16x16x32_bf16 v[10:13], v[164:167], v[212:215], v[10:13]
	v_mfma_f32_16x16x32_bf16 v[54:57], v[168:171], v[184:187], v[54:57]
	v_mfma_f32_16x16x32_bf16 v[46:49], v[176:179], v[184:187], v[46:49]
	v_mfma_f32_16x16x32_bf16 v[38:41], v[168:171], v[192:195], v[38:41]
	v_mfma_f32_16x16x32_bf16 v[30:33], v[176:179], v[192:195], v[30:33]
	v_mfma_f32_16x16x32_bf16 v[22:25], v[168:171], v[200:203], v[22:25]
	v_mfma_f32_16x16x32_bf16 v[14:17], v[176:179], v[200:203], v[14:17]
	v_mfma_f32_16x16x32_bf16 v[6:9], v[168:171], v[208:211], v[6:9]
	v_mfma_f32_16x16x32_bf16 v[2:5], v[176:179], v[208:211], v[2:5]
	v_mfma_f32_16x16x32_bf16 v[54:57], v[172:175], v[188:191], v[54:57]
	v_mfma_f32_16x16x32_bf16 v[46:49], v[180:183], v[188:191], v[46:49]
	v_mfma_f32_16x16x32_bf16 v[38:41], v[172:175], v[196:199], v[38:41]
	v_mfma_f32_16x16x32_bf16 v[30:33], v[180:183], v[196:199], v[30:33]
	v_mfma_f32_16x16x32_bf16 v[22:25], v[172:175], v[204:207], v[22:25]
	v_mfma_f32_16x16x32_bf16 v[14:17], v[180:183], v[204:207], v[14:17]
	v_mfma_f32_16x16x32_bf16 v[6:9], v[172:175], v[212:215], v[6:9]
	v_mfma_f32_16x16x32_bf16 v[2:5], v[180:183], v[212:215], v[2:5]
	s_barrier
	s_add_i32 s64, s64, 2
	s_add_u32 s62, s62, 0x100
	s_addc_u32 s63, s63, 0
	s_cmpk_gt_u32 s64, 0xdd
	s_mov_b64 s[26:27], s[28:29]
	s_cbranch_scc0 .LBB0_812
	s_and_b64 vcc, exec, s[14:15]
	s_cbranch_vccz .LBB0_815
	s_barrier

; #define PG8_STAGE(bufoff, gbase, voff) do { _Pragma("unroll") for (int _i = 0; _i < 2; ++_i) \
;         __builtin_amdgcn_global_load_lds((const unsigned*)((const char*)(gbase) + (voff)[_i]), (PG8_LAS unsigned*)(lds + (bufoff) + ldsw + _i * 8192), 16, 0, 0); } while (0)
; #define PG8_LDA(dst, b, h) do { _Pragma("unroll") for (int m = 0; m < 4; ++m) _Pragma("unroll") for (int k = 0; k < 2; ++k) dst[m][k] = *(const PG8_LAS bf16x8*)(lds + PG8_SA(b, h) + aoff + m * 2048 + k * 1024); } while (0)
; #define PG8_LDB(dst, b, h) do { _Pragma("unroll") for (int n = 0; n < 2; ++n) _Pragma("unroll") for (int k = 0; k < 2; ++k) dst[n][k] = *(const PG8_LAS bf16x8*)(lds + PG8_SB(b, h) + boff + n * 2048 + k * 1024); } while (0)
; #define PG8_MMA(ai, bj, At, Bt) do { __builtin_amdgcn_s_setprio(1); _Pragma("unroll") for (int m = 0; m < 4; ++m) _Pragma("unroll") for (int n = 0; n < 2; ++n) _Pragma("unroll") for (int k = 0; k < 2; ++k) \
;         acc[ai][bj][m][n] = __builtin_amdgcn_mfma_f32_16x16x32_bf16(Bt[n][k], At[m][k], acc[ai][bj][m][n], 0, 0, 0); __builtin_amdgcn_s_setprio(0); } while (0)
; #define PG8_WAIT_V(n) asm volatile("s_waitcnt vmcnt(" #n ")" ::: "memory")
; #define PG8_WAIT_L(n) asm volatile("s_waitcnt lgkmcnt(" #n ")" ::: "memory")
; #define PG8_BAR __builtin_amdgcn_s_barrier()
; #define PG8_SCHED __builtin_amdgcn_sched_barrier(0)
; template <class Epi, class Sched, bool ALIGN_EPI = false>
; __device__ __forceinline__ void gemm_phase(PG8_LAS unsigned char* lds, const Gemm g, const Sched& S, const Epi& E) {
;     ...
;             PG8_LDB(B0, 0, 0); PG8_LDB(B1, 0, 1); PG8_SCHED; PG8_LDA(At, 0, 0); PG8_STAGE(PG8_SA(1, 1), a1 + hstepA, voffA);
;             PG8_WAIT_V(8); PG8_WAIT_L(0); PG8_BAR; PG8_MMA(0, 0, At, B0); PG8_MMA(0, 1, At, B1); PG8_BAR; PG8_SCHED;
;             PG8_LDA(At, 0, 1); PG8_STAGE(PG8_SB(0, 0), b2, voffB); PG8_STAGE(PG8_SB(0, 1), b2 + hstepB, voffB); PG8_STAGE(PG8_SA(0, 0), a2, voffA);
;             PG8_WAIT_V(8); PG8_WAIT_L(0); PG8_BAR; PG8_MMA(1, 0, At, B0); PG8_MMA(1, 1, At, B1); PG8_BAR; PG8_SCHED;
.LBB0_933:
	ds_read_b128 v[146:149], v150
	ds_read_b128 v[154:157], v150 offset:1024
	ds_read_b128 v[158:161], v150 offset:2048
	ds_read_b128 v[162:165], v150 offset:3072
	ds_read_b128 v[166:169], v151
	ds_read_b128 v[170:173], v151 offset:1024
	ds_read_b128 v[174:177], v151 offset:2048
	ds_read_b128 v[178:181], v151 offset:3072
	s_add_u32 s26, s24, 0xfff00080
	s_addc_u32 s27, s25, -1
	s_cmp_eq_u32 s52, 60
	s_cselect_b32 s29, s17, s27
	s_cselect_b32 s28, s48, s26
	s_cselect_b32 s27, s15, s51
	s_cselect_b32 s26, s49, s50
	s_add_i32 m0, s23, 0xc000
	ds_read_b128 v[182:185], v152
	ds_read_b128 v[186:189], v152 offset:1024
	ds_read_b128 v[190:193], v152 offset:2048
	ds_read_b128 v[194:197], v152 offset:3072
	ds_read_b128 v[198:201], v152 offset:4096
	ds_read_b128 v[202:205], v152 offset:5120
	ds_read_b128 v[206:209], v152 offset:6144
	ds_read_b128 v[210:213], v152 offset:7168
	global_load_lds_dwordx4 v138, s[24:25]
	s_add_i32 m0, s23, 0xe000
	s_nop 0
	global_load_lds_dwordx4 v140, s[24:25]
	s_waitcnt vmcnt(8)
	s_waitcnt lgkmcnt(0)
	s_barrier
	s_waitcnt lgkmcnt(0)
	v_mfma_f32_16x16x32_bf16 v[126:129], v[146:149], v[182:185], v[126:129]
	v_mfma_f32_16x16x32_bf16 v[122:125], v[158:161], v[182:185], v[122:125]
	v_mfma_f32_16x16x32_bf16 v[118:121], v[146:149], v[190:193], v[118:121]
	v_mfma_f32_16x16x32_bf16 v[110:113], v[158:161], v[190:193], v[110:113]
	v_mfma_f32_16x16x32_bf16 v[102:105], v[146:149], v[198:201], v[102:105]
	v_mfma_f32_16x16x32_bf16 v[94:97], v[158:161], v[198:201], v[94:97]
	v_mfma_f32_16x16x32_bf16 v[86:89], v[146:149], v[206:209], v[86:89]
	v_mfma_f32_16x16x32_bf16 v[78:81], v[158:161], v[206:209], v[78:81]
	v_mfma_f32_16x16x32_bf16 v[126:129], v[154:157], v[186:189], v[126:129]
	v_mfma_f32_16x16x32_bf16 v[122:125], v[162:165], v[186:189], v[122:125]
	v_mfma_f32_16x16x32_bf16 v[118:121], v[154:157], v[194:197], v[118:121]
	v_mfma_f32_16x16x32_bf16 v[110:113], v[162:165], v[194:197], v[110:113]
	v_mfma_f32_16x16x32_bf16 v[102:105], v[154:157], v[202:205], v[102:105]
	v_mfma_f32_16x16x32_bf16 v[94:97], v[162:165], v[202:205], v[94:97]
	v_mfma_f32_16x16x32_bf16 v[86:89], v[154:157], v[210:213], v[86:89]
	v_mfma_f32_16x16x32_bf16 v[78:81], v[162:165], v[210:213], v[78:81]
	v_mfma_f32_16x16x32_bf16 v[114:117], v[166:169], v[182:185], v[114:117]
	v_mfma_f32_16x16x32_bf16 v[106:109], v[174:177], v[182:185], v[106:109]
	v_mfma_f32_16x16x32_bf16 v[98:101], v[166:169], v[190:193], v[98:101]
	v_mfma_f32_16x16x32_bf16 v[90:93], v[174:177], v[190:193], v[90:93]
	v_mfma_f32_16x16x32_bf16 v[82:85], v[166:169], v[198:201], v[82:85]
	v_mfma_f32_16x16x32_bf16 v[74:77], v[174:177], v[198:201], v[74:77]
	v_mfma_f32_16x16x32_bf16 v[70:73], v[166:169], v[206:209], v[70:73]
	v_mfma_f32_16x16x32_bf16 v[66:69], v[174:177], v[206:209], v[66:69]
	v_mfma_f32_16x16x32_bf16 v[114:117], v[170:173], v[186:189], v[114:117]
	v_mfma_f32_16x16x32_bf16 v[106:109], v[178:181], v[186:189], v[106:109]
	v_mfma_f32_16x16x32_bf16 v[98:101], v[170:173], v[194:197], v[98:101]
	v_mfma_f32_16x16x32_bf16 v[90:93], v[178:181], v[194:197], v[90:93]
	v_mfma_f32_16x16x32_bf16 v[82:85], v[170:173], v[202:205], v[82:85]
	v_mfma_f32_16x16x32_bf16 v[74:77], v[178:181], v[202:205], v[74:77]
	v_mfma_f32_16x16x32_bf16 v[70:73], v[170:173], v[210:213], v[70:73]
	v_mfma_f32_16x16x32_bf16 v[66:69], v[178:181], v[210:213], v[66:69]
	s_barrier
	s_add_i32 s53, s44, s34
	s_add_u32 s98, s26, s10
	s_addc_u32 s99, s27, s11
	s_mov_b32 m0, s53
	ds_read_b128 v[182:185], v152 offset:16384
	ds_read_b128 v[186:189], v152 offset:17408
	ds_read_b128 v[190:193], v152 offset:18432
	ds_read_b128 v[194:197], v152 offset:19456
	ds_read_b128 v[198:201], v152 offset:20480
	ds_read_b128 v[202:205], v152 offset:21504
	ds_read_b128 v[206:209], v152 offset:22528
	ds_read_b128 v[210:213], v152 offset:23552
	global_load_lds_dwordx4 v134, s[26:27]
	s_add_i32 m0, s53, 0x2000
	s_add_u32 s54, s26, 0x100000
	s_addc_u32 s55, s27, 0
	s_add_i32 s53, s45, s34
	global_load_lds_dwordx4 v130, s[26:27]
	s_mov_b32 m0, s53
	s_nop 0
	global_load_lds_dwordx4 v134, s[54:55]
	s_add_i32 m0, s53, 0x2000
	s_nop 0
	global_load_lds_dwordx4 v130, s[54:55]
	s_add_u32 s100, s28, s10
	s_addc_u32 s101, s29, s11
	s_mov_b32 m0, s23
	s_nop 0
	global_load_lds_dwordx4 v136, s[28:29]
	s_mov_b32 m0, s37
	s_nop 0
	global_load_lds_dwordx4 v132, s[28:29]
	s_waitcnt vmcnt(8)
	s_waitcnt lgkmcnt(0)
	s_barrier
	s_waitcnt lgkmcnt(0)
	v_mfma_f32_16x16x32_bf16 v[62:65], v[146:149], v[182:185], v[62:65]
	v_mfma_f32_16x16x32_bf16 v[58:61], v[158:161], v[182:185], v[58:61]
	v_mfma_f32_16x16x32_bf16 v[54:57], v[146:149], v[190:193], v[54:57]
	v_mfma_f32_16x16x32_bf16 v[46:49], v[158:161], v[190:193], v[46:49]
	v_mfma_f32_16x16x32_bf16 v[38:41], v[146:149], v[198:201], v[38:41]
	v_mfma_f32_16x16x32_bf16 v[30:33], v[158:161], v[198:201], v[30:33]
	v_mfma_f32_16x16x32_bf16 v[22:25], v[146:149], v[206:209], v[22:25]
	v_mfma_f32_16x16x32_bf16 v[14:17], v[158:161], v[206:209], v[14:17]
	v_mfma_f32_16x16x32_bf16 v[62:65], v[154:157], v[186:189], v[62:65]
	v_mfma_f32_16x16x32_bf16 v[58:61], v[162:165], v[186:189], v[58:61]
	v_mfma_f32_16x16x32_bf16 v[54:57], v[154:157], v[194:197], v[54:57]
	v_mfma_f32_16x16x32_bf16 v[46:49], v[162:165], v[194:197], v[46:49]
	v_mfma_f32_16x16x32_bf16 v[38:41], v[154:157], v[202:205], v[38:41]
	v_mfma_f32_16x16x32_bf16 v[30:33], v[162:165], v[202:205], v[30:33]
	v_mfma_f32_16x16x32_bf16 v[22:25], v[154:157], v[210:213], v[22:25]
	v_mfma_f32_16x16x32_bf16 v[14:17], v[162:165], v[210:213], v[14:17]
	v_mfma_f32_16x16x32_bf16 v[50:53], v[166:169], v[182:185], v[50:53]
	v_mfma_f32_16x16x32_bf16 v[42:45], v[174:177], v[182:185], v[42:45]
	v_mfma_f32_16x16x32_bf16 v[34:37], v[166:169], v[190:193], v[34:37]
	v_mfma_f32_16x16x32_bf16 v[26:29], v[174:177], v[190:193], v[26:29]
	v_mfma_f32_16x16x32_bf16 v[18:21], v[166:169], v[198:201], v[18:21]
	v_mfma_f32_16x16x32_bf16 v[10:13], v[174:177], v[198:201], v[10:13]
	v_mfma_f32_16x16x32_bf16 v[6:9], v[166:169], v[206:209], v[6:9]
	v_mfma_f32_16x16x32_bf16 v[2:5], v[174:177], v[206:209], v[2:5]
	v_mfma_f32_16x16x32_bf16 v[50:53], v[170:173], v[186:189], v[50:53]
	v_mfma_f32_16x16x32_bf16 v[42:45], v[178:181], v[186:189], v[42:45]
	v_mfma_f32_16x16x32_bf16 v[34:37], v[170:173], v[194:197], v[34:37]
	v_mfma_f32_16x16x32_bf16 v[26:29], v[178:181], v[194:197], v[26:29]
	v_mfma_f32_16x16x32_bf16 v[18:21], v[170:173], v[202:205], v[18:21]
	v_mfma_f32_16x16x32_bf16 v[10:13], v[178:181], v[202:205], v[10:13]
	v_mfma_f32_16x16x32_bf16 v[6:9], v[170:173], v[210:213], v[6:9]
	v_mfma_f32_16x16x32_bf16 v[2:5], v[178:181], v[210:213], v[2:5]
	s_barrier
; #define PG8_STAGE(bufoff, gbase, voff) do { _Pragma("unroll") for (int _i = 0; _i < 2; ++_i) \
;         __builtin_amdgcn_global_load_lds((const unsigned*)((const char*)(gbase) + (voff)[_i]), (PG8_LAS unsigned*)(lds + (bufoff) + ldsw + _i * 8192), 16, 0, 0); } while (0)
; #define PG8_LDA(dst, b, h) do { _Pragma("unroll") for (int m = 0; m < 4; ++m) _Pragma("unroll") for (int k = 0; k < 2; ++k) dst[m][k] = *(const PG8_LAS bf16x8*)(lds + PG8_SA(b, h) + aoff + m * 2048 + k * 1024); } while (0)
; #define PG8_LDB(dst, b, h) do { _Pragma("unroll") for (int n = 0; n < 2; ++n) _Pragma("unroll") for (int k = 0; k < 2; ++k) dst[n][k] = *(const PG8_LAS bf16x8*)(lds + PG8_SB(b, h) + boff + n * 2048 + k * 1024); } while (0)
; #define PG8_MMA(ai, bj, At, Bt) do { __builtin_amdgcn_s_setprio(1); _Pragma("unroll") for (int m = 0; m < 4; ++m) _Pragma("unroll") for (int n = 0; n < 2; ++n) _Pragma("unroll") for (int k = 0; k < 2; ++k) \
;         acc[ai][bj][m][n] = __builtin_amdgcn_mfma_f32_16x16x32_bf16(Bt[n][k], At[m][k], acc[ai][bj][m][n], 0, 0, 0); __builtin_amdgcn_s_setprio(0); } while (0)
; #define PG8_WAIT_V(n) asm volatile("s_waitcnt vmcnt(" #n ")" ::: "memory")
; #define PG8_WAIT_L(n) asm volatile("s_waitcnt lgkmcnt(" #n ")" ::: "memory")
; #define PG8_BAR __builtin_amdgcn_s_barrier()
; #define PG8_SCHED __builtin_amdgcn_sched_barrier(0)
; template <class Epi, class Sched, bool ALIGN_EPI = false>
; __device__ __forceinline__ void gemm_phase(PG8_LAS unsigned char* lds, const Gemm g, const Sched& S, const Epi& E) {
;     ...
;             PG8_LDB(B0, 1, 0); PG8_LDB(B1, 1, 1); PG8_SCHED; PG8_LDA(At, 1, 0); PG8_STAGE(PG8_SA(0, 1), a2 + hstepA, voffA);
;             PG8_WAIT_V(8); PG8_WAIT_L(0); PG8_BAR; PG8_MMA(0, 0, At, B0); PG8_MMA(0, 1, At, B1); PG8_BAR; PG8_SCHED;
;             PG8_LDA(At, 1, 1); PG8_STAGE(PG8_SB(1, 0), b3, voffB); PG8_STAGE(PG8_SB(1, 1), b3 + hstepB, voffB); PG8_STAGE(PG8_SA(1, 0), a3, voffA);
;             PG8_WAIT_V(8); PG8_WAIT_L(0); PG8_BAR; PG8_MMA(1, 0, At, B0); PG8_MMA(1, 1, At, B1); PG8_BAR; PG8_SCHED;
;         }
;         if constexpr (ALIGN_EPI) { if (wr == 0) PG8_BAR; }
	s_add_i32 s53, 0, 0x18000
	v_add_u32_e32 v153, s53, v1
	s_add_i32 s54, 0, 0x1c000
	ds_read_b128 v[146:149], v153
	ds_read_b128 v[154:157], v153 offset:1024
	ds_read_b128 v[158:161], v153 offset:2048
	ds_read_b128 v[162:165], v153 offset:3072
	v_add_u32_e32 v153, s54, v1
	ds_read_b128 v[166:169], v153
	ds_read_b128 v[170:173], v153 offset:1024
	ds_read_b128 v[174:177], v153 offset:2048
	ds_read_b128 v[178:181], v153 offset:3072
	s_add_u32 s28, s28, 0x100000
	s_addc_u32 s29, s29, 0
	s_mov_b32 m0, s38
	ds_read_b128 v[182:185], v152 offset:32768
	ds_read_b128 v[186:189], v152 offset:33792
	ds_read_b128 v[190:193], v152 offset:34816
	ds_read_b128 v[194:197], v152 offset:35840
	ds_read_b128 v[198:201], v152 offset:36864
	ds_read_b128 v[202:205], v152 offset:37888
	ds_read_b128 v[206:209], v152 offset:38912
	ds_read_b128 v[210:213], v152 offset:39936
	global_load_lds_dwordx4 v136, s[28:29]
	s_mov_b32 m0, s39
	s_nop 0
	global_load_lds_dwordx4 v132, s[28:29]
	s_waitcnt vmcnt(8)
	s_waitcnt lgkmcnt(0)
	s_barrier
	s_waitcnt lgkmcnt(0)
	v_mfma_f32_16x16x32_bf16 v[126:129], v[146:149], v[182:185], v[126:129]
	v_mfma_f32_16x16x32_bf16 v[122:125], v[158:161], v[182:185], v[122:125]
	v_mfma_f32_16x16x32_bf16 v[118:121], v[146:149], v[190:193], v[118:121]
	v_mfma_f32_16x16x32_bf16 v[110:113], v[158:161], v[190:193], v[110:113]
	v_mfma_f32_16x16x32_bf16 v[102:105], v[146:149], v[198:201], v[102:105]
	v_mfma_f32_16x16x32_bf16 v[94:97], v[158:161], v[198:201], v[94:97]
	v_mfma_f32_16x16x32_bf16 v[86:89], v[146:149], v[206:209], v[86:89]
	v_mfma_f32_16x16x32_bf16 v[78:81], v[158:161], v[206:209], v[78:81]
	v_mfma_f32_16x16x32_bf16 v[126:129], v[154:157], v[186:189], v[126:129]
	v_mfma_f32_16x16x32_bf16 v[122:125], v[162:165], v[186:189], v[122:125]
	v_mfma_f32_16x16x32_bf16 v[118:121], v[154:157], v[194:197], v[118:121]
	v_mfma_f32_16x16x32_bf16 v[110:113], v[162:165], v[194:197], v[110:113]
	v_mfma_f32_16x16x32_bf16 v[102:105], v[154:157], v[202:205], v[102:105]
	v_mfma_f32_16x16x32_bf16 v[94:97], v[162:165], v[202:205], v[94:97]
	v_mfma_f32_16x16x32_bf16 v[86:89], v[154:157], v[210:213], v[86:89]
	v_mfma_f32_16x16x32_bf16 v[78:81], v[162:165], v[210:213], v[78:81]
	v_mfma_f32_16x16x32_bf16 v[114:117], v[166:169], v[182:185], v[114:117]
	v_mfma_f32_16x16x32_bf16 v[106:109], v[174:177], v[182:185], v[106:109]
	v_mfma_f32_16x16x32_bf16 v[98:101], v[166:169], v[190:193], v[98:101]
	v_mfma_f32_16x16x32_bf16 v[90:93], v[174:177], v[190:193], v[90:93]
	v_mfma_f32_16x16x32_bf16 v[82:85], v[166:169], v[198:201], v[82:85]
	v_mfma_f32_16x16x32_bf16 v[74:77], v[174:177], v[198:201], v[74:77]
	v_mfma_f32_16x16x32_bf16 v[70:73], v[166:169], v[206:209], v[70:73]
	v_mfma_f32_16x16x32_bf16 v[66:69], v[174:177], v[206:209], v[66:69]
	v_mfma_f32_16x16x32_bf16 v[114:117], v[170:173], v[186:189], v[114:117]
	v_mfma_f32_16x16x32_bf16 v[106:109], v[178:181], v[186:189], v[106:109]
	v_mfma_f32_16x16x32_bf16 v[98:101], v[170:173], v[194:197], v[98:101]
	v_mfma_f32_16x16x32_bf16 v[90:93], v[178:181], v[194:197], v[90:93]
	v_mfma_f32_16x16x32_bf16 v[82:85], v[170:173], v[202:205], v[82:85]
	v_mfma_f32_16x16x32_bf16 v[74:77], v[178:181], v[202:205], v[74:77]
	v_mfma_f32_16x16x32_bf16 v[70:73], v[170:173], v[210:213], v[70:73]
	v_mfma_f32_16x16x32_bf16 v[66:69], v[178:181], v[210:213], v[66:69]
	s_barrier
	s_add_i32 s28, s53, s34
	s_mov_b32 m0, s28
	ds_read_b128 v[182:185], v152 offset:49152
	ds_read_b128 v[186:189], v152 offset:50176
	ds_read_b128 v[190:193], v152 offset:51200
	ds_read_b128 v[194:197], v152 offset:52224
	ds_read_b128 v[198:201], v152 offset:53248
	ds_read_b128 v[202:205], v152 offset:54272
	ds_read_b128 v[206:209], v152 offset:55296
	ds_read_b128 v[210:213], v152 offset:56320
	global_load_lds_dwordx4 v134, s[98:99]
	s_add_i32 m0, s28, 0x2000
	s_add_u32 s26, s26, 0x100080
	s_addc_u32 s27, s27, 0
	s_add_i32 s28, s54, s34
	global_load_lds_dwordx4 v130, s[98:99]
	s_mov_b32 m0, s28
	s_nop 0
	global_load_lds_dwordx4 v134, s[26:27]
	s_add_i32 m0, s28, 0x2000
	s_nop 0
	global_load_lds_dwordx4 v130, s[26:27]
	s_mov_b32 m0, s41
	s_nop 0
	global_load_lds_dwordx4 v136, s[100:101]
	s_mov_b32 m0, s42
	s_nop 0
	global_load_lds_dwordx4 v132, s[100:101]
	s_waitcnt vmcnt(8)
	s_waitcnt lgkmcnt(0)
	s_barrier
	s_waitcnt lgkmcnt(0)
	v_mfma_f32_16x16x32_bf16 v[62:65], v[146:149], v[182:185], v[62:65]
	v_mfma_f32_16x16x32_bf16 v[58:61], v[158:161], v[182:185], v[58:61]
	v_mfma_f32_16x16x32_bf16 v[54:57], v[146:149], v[190:193], v[54:57]
	v_mfma_f32_16x16x32_bf16 v[46:49], v[158:161], v[190:193], v[46:49]
	v_mfma_f32_16x16x32_bf16 v[38:41], v[146:149], v[198:201], v[38:41]
	v_mfma_f32_16x16x32_bf16 v[30:33], v[158:161], v[198:201], v[30:33]
	v_mfma_f32_16x16x32_bf16 v[22:25], v[146:149], v[206:209], v[22:25]
	v_mfma_f32_16x16x32_bf16 v[14:17], v[158:161], v[206:209], v[14:17]
	v_mfma_f32_16x16x32_bf16 v[62:65], v[154:157], v[186:189], v[62:65]
	v_mfma_f32_16x16x32_bf16 v[58:61], v[162:165], v[186:189], v[58:61]
	v_mfma_f32_16x16x32_bf16 v[54:57], v[154:157], v[194:197], v[54:57]
	v_mfma_f32_16x16x32_bf16 v[46:49], v[162:165], v[194:197], v[46:49]
	v_mfma_f32_16x16x32_bf16 v[38:41], v[154:157], v[202:205], v[38:41]
	v_mfma_f32_16x16x32_bf16 v[30:33], v[162:165], v[202:205], v[30:33]
	v_mfma_f32_16x16x32_bf16 v[22:25], v[154:157], v[210:213], v[22:25]
	v_mfma_f32_16x16x32_bf16 v[14:17], v[162:165], v[210:213], v[14:17]
	v_mfma_f32_16x16x32_bf16 v[50:53], v[166:169], v[182:185], v[50:53]
	v_mfma_f32_16x16x32_bf16 v[42:45], v[174:177], v[182:185], v[42:45]
	v_mfma_f32_16x16x32_bf16 v[34:37], v[166:169], v[190:193], v[34:37]
	v_mfma_f32_16x16x32_bf16 v[26:29], v[174:177], v[190:193], v[26:29]
	v_mfma_f32_16x16x32_bf16 v[18:21], v[166:169], v[198:201], v[18:21]
	v_mfma_f32_16x16x32_bf16 v[10:13], v[174:177], v[198:201], v[10:13]
	v_mfma_f32_16x16x32_bf16 v[6:9], v[166:169], v[206:209], v[6:9]
	v_mfma_f32_16x16x32_bf16 v[2:5], v[174:177], v[206:209], v[2:5]
	v_mfma_f32_16x16x32_bf16 v[50:53], v[170:173], v[186:189], v[50:53]
	v_mfma_f32_16x16x32_bf16 v[42:45], v[178:181], v[186:189], v[42:45]
	v_mfma_f32_16x16x32_bf16 v[34:37], v[170:173], v[194:197], v[34:37]
	v_mfma_f32_16x16x32_bf16 v[26:29], v[178:181], v[194:197], v[26:29]
	v_mfma_f32_16x16x32_bf16 v[18:21], v[170:173], v[202:205], v[18:21]
	v_mfma_f32_16x16x32_bf16 v[10:13], v[178:181], v[202:205], v[10:13]
	v_mfma_f32_16x16x32_bf16 v[6:9], v[170:173], v[210:213], v[6:9]
	v_mfma_f32_16x16x32_bf16 v[2:5], v[178:181], v[210:213], v[2:5]
	s_barrier
	s_add_i32 s52, s52, 2
	s_add_u32 s24, s24, 0x100
	s_addc_u32 s25, s25, 0
	s_add_u32 s50, s50, 0x100
	s_addc_u32 s51, s51, 0
	s_cmp_gt_u32 s52, 61
	s_cbranch_scc0 .LBB0_933
	s_and_b64 vcc, exec, s[12:13]
	s_cbranch_vccz .LBB0_936
	s_barrier

; #define PG8_STAGE(bufoff, gbase, voff) do { _Pragma("unroll") for (int _i = 0; _i < 2; ++_i) \
;         __builtin_amdgcn_global_load_lds((const unsigned*)((const char*)(gbase) + (voff)[_i]), (PG8_LAS unsigned*)(lds + (bufoff) + ldsw + _i * 8192), 16, 0, 0); } while (0)
; #define PG8_LDA(dst, b, h) do { _Pragma("unroll") for (int m = 0; m < 4; ++m) _Pragma("unroll") for (int k = 0; k < 2; ++k) dst[m][k] = *(const PG8_LAS bf16x8*)(lds + PG8_SA(b, h) + aoff + m * 2048 + k * 1024); } while (0)
; #define PG8_LDB(dst, b, h) do { _Pragma("unroll") for (int n = 0; n < 2; ++n) _Pragma("unroll") for (int k = 0; k < 2; ++k) dst[n][k] = *(const PG8_LAS bf16x8*)(lds + PG8_SB(b, h) + boff + n * 2048 + k * 1024); } while (0)
; #define PG8_MMA(ai, bj, At, Bt) do { __builtin_amdgcn_s_setprio(1); _Pragma("unroll") for (int m = 0; m < 4; ++m) _Pragma("unroll") for (int n = 0; n < 2; ++n) _Pragma("unroll") for (int k = 0; k < 2; ++k) \
;         acc[ai][bj][m][n] = __builtin_amdgcn_mfma_f32_16x16x32_bf16(Bt[n][k], At[m][k], acc[ai][bj][m][n], 0, 0, 0); __builtin_amdgcn_s_setprio(0); } while (0)
; #define PG8_WAIT_V(n) asm volatile("s_waitcnt vmcnt(" #n ")" ::: "memory")
; #define PG8_WAIT_L(n) asm volatile("s_waitcnt lgkmcnt(" #n ")" ::: "memory")
; #define PG8_BAR __builtin_amdgcn_s_barrier()
; #define PG8_SCHED __builtin_amdgcn_sched_barrier(0)
; template <class Epi, class Sched, bool ALIGN_EPI = false>
; __device__ __forceinline__ void gemm_phase(PG8_LAS unsigned char* lds, const Gemm g, const Sched& S, const Epi& E) {
;     ...
;             PG8_LDB(B0, 0, 0); PG8_LDB(B1, 0, 1); PG8_SCHED; PG8_LDA(At, 0, 0); PG8_STAGE(PG8_SA(1, 1), a1 + hstepA, voffA);
;             PG8_WAIT_V(8); PG8_WAIT_L(0); PG8_BAR; PG8_MMA(0, 0, At, B0); PG8_MMA(0, 1, At, B1); PG8_BAR; PG8_SCHED;
;             PG8_LDA(At, 0, 1); PG8_STAGE(PG8_SB(0, 0), b2, voffB); PG8_STAGE(PG8_SB(0, 1), b2 + hstepB, voffB); PG8_STAGE(PG8_SA(0, 0), a2, voffA);
;             PG8_WAIT_V(8); PG8_WAIT_L(0); PG8_BAR; PG8_MMA(1, 0, At, B0); PG8_MMA(1, 1, At, B1); PG8_BAR; PG8_SCHED;
.LBB0_1423:
	ds_read_b128 v[146:149], v152
	ds_read_b128 v[156:159], v152 offset:1024
	ds_read_b128 v[160:163], v152 offset:2048
	ds_read_b128 v[164:167], v152 offset:3072
	ds_read_b128 v[168:171], v153
	ds_read_b128 v[172:175], v153 offset:1024
	ds_read_b128 v[176:179], v153 offset:2048
	ds_read_b128 v[180:183], v153 offset:3072
	s_add_u32 s36, s34, 0xfff00080
	s_addc_u32 s37, s35, -1
	s_cmp_eq_u32 s66, 60
	s_cselect_b32 s39, s25, s37
	s_cselect_b32 s38, s62, s36
	s_cselect_b32 s37, s23, s65
	s_cselect_b32 s36, s63, s64
	s_add_i32 m0, s31, 0xc000
	ds_read_b128 v[184:187], v154
	ds_read_b128 v[188:191], v154 offset:1024
	ds_read_b128 v[192:195], v154 offset:2048
	ds_read_b128 v[196:199], v154 offset:3072
	ds_read_b128 v[200:203], v154 offset:4096
	ds_read_b128 v[204:207], v154 offset:5120
	ds_read_b128 v[208:211], v154 offset:6144
	ds_read_b128 v[212:215], v154 offset:7168
	global_load_lds_dwordx4 v138, s[34:35]
	s_add_i32 m0, s31, 0xe000
	s_nop 0
	global_load_lds_dwordx4 v140, s[34:35]
	s_waitcnt vmcnt(8)
	s_waitcnt lgkmcnt(0)
	s_barrier
	s_waitcnt lgkmcnt(0)
	v_mfma_f32_16x16x32_bf16 v[126:129], v[146:149], v[184:187], v[126:129]
	v_mfma_f32_16x16x32_bf16 v[122:125], v[160:163], v[184:187], v[122:125]
	v_mfma_f32_16x16x32_bf16 v[114:117], v[146:149], v[192:195], v[114:117]
	v_mfma_f32_16x16x32_bf16 v[106:109], v[160:163], v[192:195], v[106:109]
	v_mfma_f32_16x16x32_bf16 v[98:101], v[146:149], v[200:203], v[98:101]
	v_mfma_f32_16x16x32_bf16 v[90:93], v[160:163], v[200:203], v[90:93]
	v_mfma_f32_16x16x32_bf16 v[82:85], v[146:149], v[208:211], v[82:85]
	v_mfma_f32_16x16x32_bf16 v[74:77], v[160:163], v[208:211], v[74:77]
	v_mfma_f32_16x16x32_bf16 v[126:129], v[156:159], v[188:191], v[126:129]
	v_mfma_f32_16x16x32_bf16 v[122:125], v[164:167], v[188:191], v[122:125]
	v_mfma_f32_16x16x32_bf16 v[114:117], v[156:159], v[196:199], v[114:117]
	v_mfma_f32_16x16x32_bf16 v[106:109], v[164:167], v[196:199], v[106:109]
	v_mfma_f32_16x16x32_bf16 v[98:101], v[156:159], v[204:207], v[98:101]
	v_mfma_f32_16x16x32_bf16 v[90:93], v[164:167], v[204:207], v[90:93]
	v_mfma_f32_16x16x32_bf16 v[82:85], v[156:159], v[212:215], v[82:85]
	v_mfma_f32_16x16x32_bf16 v[74:77], v[164:167], v[212:215], v[74:77]
	v_mfma_f32_16x16x32_bf16 v[118:121], v[168:171], v[184:187], v[118:121]
	v_mfma_f32_16x16x32_bf16 v[110:113], v[176:179], v[184:187], v[110:113]
	v_mfma_f32_16x16x32_bf16 v[102:105], v[168:171], v[192:195], v[102:105]
	v_mfma_f32_16x16x32_bf16 v[94:97], v[176:179], v[192:195], v[94:97]
	v_mfma_f32_16x16x32_bf16 v[86:89], v[168:171], v[200:203], v[86:89]
	v_mfma_f32_16x16x32_bf16 v[78:81], v[176:179], v[200:203], v[78:81]
	v_mfma_f32_16x16x32_bf16 v[70:73], v[168:171], v[208:211], v[70:73]
	v_mfma_f32_16x16x32_bf16 v[66:69], v[176:179], v[208:211], v[66:69]
	v_mfma_f32_16x16x32_bf16 v[118:121], v[172:175], v[188:191], v[118:121]
	v_mfma_f32_16x16x32_bf16 v[110:113], v[180:183], v[188:191], v[110:113]
	v_mfma_f32_16x16x32_bf16 v[102:105], v[172:175], v[196:199], v[102:105]
	v_mfma_f32_16x16x32_bf16 v[94:97], v[180:183], v[196:199], v[94:97]
	v_mfma_f32_16x16x32_bf16 v[86:89], v[172:175], v[204:207], v[86:89]
	v_mfma_f32_16x16x32_bf16 v[78:81], v[180:183], v[204:207], v[78:81]
	v_mfma_f32_16x16x32_bf16 v[70:73], v[172:175], v[212:215], v[70:73]
	v_mfma_f32_16x16x32_bf16 v[66:69], v[180:183], v[212:215], v[66:69]
	s_barrier
	s_add_i32 s67, s51, s43
	s_add_u32 s98, s36, s12
	s_addc_u32 s99, s37, s13
	s_mov_b32 m0, s67
	ds_read_b128 v[184:187], v154 offset:16384
	ds_read_b128 v[188:191], v154 offset:17408
	ds_read_b128 v[192:195], v154 offset:18432
	ds_read_b128 v[196:199], v154 offset:19456
	ds_read_b128 v[200:203], v154 offset:20480
	ds_read_b128 v[204:207], v154 offset:21504
	ds_read_b128 v[208:211], v154 offset:22528
	ds_read_b128 v[212:215], v154 offset:23552
	global_load_lds_dwordx4 v132, s[36:37]
	s_add_i32 m0, s67, 0x2000
	s_add_u32 s68, s36, 0x100000
	s_addc_u32 s69, s37, 0
	s_add_i32 s67, s52, s43
	global_load_lds_dwordx4 v136, s[36:37]
	s_mov_b32 m0, s67
	s_nop 0
	global_load_lds_dwordx4 v132, s[68:69]
	s_add_i32 m0, s67, 0x2000
	s_nop 0
	global_load_lds_dwordx4 v136, s[68:69]
	s_add_u32 s100, s38, s12
	s_addc_u32 s101, s39, s13
	s_mov_b32 m0, s31
	s_nop 0
	global_load_lds_dwordx4 v130, s[38:39]
	s_mov_b32 m0, s44
	s_nop 0
	global_load_lds_dwordx4 v134, s[38:39]
	s_waitcnt vmcnt(8)
	s_waitcnt lgkmcnt(0)
	s_barrier
	s_waitcnt lgkmcnt(0)
	v_mfma_f32_16x16x32_bf16 v[62:65], v[146:149], v[184:187], v[62:65]
	v_mfma_f32_16x16x32_bf16 v[58:61], v[160:163], v[184:187], v[58:61]
	v_mfma_f32_16x16x32_bf16 v[50:53], v[146:149], v[192:195], v[50:53]
	v_mfma_f32_16x16x32_bf16 v[42:45], v[160:163], v[192:195], v[42:45]
	v_mfma_f32_16x16x32_bf16 v[34:37], v[146:149], v[200:203], v[34:37]
	v_mfma_f32_16x16x32_bf16 v[26:29], v[160:163], v[200:203], v[26:29]
	v_mfma_f32_16x16x32_bf16 v[18:21], v[146:149], v[208:211], v[18:21]
	v_mfma_f32_16x16x32_bf16 v[10:13], v[160:163], v[208:211], v[10:13]
	v_mfma_f32_16x16x32_bf16 v[62:65], v[156:159], v[188:191], v[62:65]
	v_mfma_f32_16x16x32_bf16 v[58:61], v[164:167], v[188:191], v[58:61]
	v_mfma_f32_16x16x32_bf16 v[50:53], v[156:159], v[196:199], v[50:53]
	v_mfma_f32_16x16x32_bf16 v[42:45], v[164:167], v[196:199], v[42:45]
	v_mfma_f32_16x16x32_bf16 v[34:37], v[156:159], v[204:207], v[34:37]
	v_mfma_f32_16x16x32_bf16 v[26:29], v[164:167], v[204:207], v[26:29]
	v_mfma_f32_16x16x32_bf16 v[18:21], v[156:159], v[212:215], v[18:21]
	v_mfma_f32_16x16x32_bf16 v[10:13], v[164:167], v[212:215], v[10:13]
	v_mfma_f32_16x16x32_bf16 v[54:57], v[168:171], v[184:187], v[54:57]
	v_mfma_f32_16x16x32_bf16 v[46:49], v[176:179], v[184:187], v[46:49]
	v_mfma_f32_16x16x32_bf16 v[38:41], v[168:171], v[192:195], v[38:41]
	v_mfma_f32_16x16x32_bf16 v[30:33], v[176:179], v[192:195], v[30:33]
	v_mfma_f32_16x16x32_bf16 v[22:25], v[168:171], v[200:203], v[22:25]
	v_mfma_f32_16x16x32_bf16 v[14:17], v[176:179], v[200:203], v[14:17]
	v_mfma_f32_16x16x32_bf16 v[6:9], v[168:171], v[208:211], v[6:9]
	v_mfma_f32_16x16x32_bf16 v[2:5], v[176:179], v[208:211], v[2:5]
	v_mfma_f32_16x16x32_bf16 v[54:57], v[172:175], v[188:191], v[54:57]
	v_mfma_f32_16x16x32_bf16 v[46:49], v[180:183], v[188:191], v[46:49]
	v_mfma_f32_16x16x32_bf16 v[38:41], v[172:175], v[196:199], v[38:41]
	v_mfma_f32_16x16x32_bf16 v[30:33], v[180:183], v[196:199], v[30:33]
	v_mfma_f32_16x16x32_bf16 v[22:25], v[172:175], v[204:207], v[22:25]
	v_mfma_f32_16x16x32_bf16 v[14:17], v[180:183], v[204:207], v[14:17]
	v_mfma_f32_16x16x32_bf16 v[6:9], v[172:175], v[212:215], v[6:9]
	v_mfma_f32_16x16x32_bf16 v[2:5], v[180:183], v[212:215], v[2:5]
	s_barrier
; #define PG8_STAGE(bufoff, gbase, voff) do { _Pragma("unroll") for (int _i = 0; _i < 2; ++_i) \
;         __builtin_amdgcn_global_load_lds((const unsigned*)((const char*)(gbase) + (voff)[_i]), (PG8_LAS unsigned*)(lds + (bufoff) + ldsw + _i * 8192), 16, 0, 0); } while (0)
; #define PG8_LDA(dst, b, h) do { _Pragma("unroll") for (int m = 0; m < 4; ++m) _Pragma("unroll") for (int k = 0; k < 2; ++k) dst[m][k] = *(const PG8_LAS bf16x8*)(lds + PG8_SA(b, h) + aoff + m * 2048 + k * 1024); } while (0)
; #define PG8_LDB(dst, b, h) do { _Pragma("unroll") for (int n = 0; n < 2; ++n) _Pragma("unroll") for (int k = 0; k < 2; ++k) dst[n][k] = *(const PG8_LAS bf16x8*)(lds + PG8_SB(b, h) + boff + n * 2048 + k * 1024); } while (0)
; #define PG8_MMA(ai, bj, At, Bt) do { __builtin_amdgcn_s_setprio(1); _Pragma("unroll") for (int m = 0; m < 4; ++m) _Pragma("unroll") for (int n = 0; n < 2; ++n) _Pragma("unroll") for (int k = 0; k < 2; ++k) \
;         acc[ai][bj][m][n] = __builtin_amdgcn_mfma_f32_16x16x32_bf16(Bt[n][k], At[m][k], acc[ai][bj][m][n], 0, 0, 0); __builtin_amdgcn_s_setprio(0); } while (0)
; #define PG8_WAIT_V(n) asm volatile("s_waitcnt vmcnt(" #n ")" ::: "memory")
; #define PG8_WAIT_L(n) asm volatile("s_waitcnt lgkmcnt(" #n ")" ::: "memory")
; #define PG8_BAR __builtin_amdgcn_s_barrier()
; #define PG8_SCHED __builtin_amdgcn_sched_barrier(0)
; template <class Epi, class Sched, bool ALIGN_EPI = false>
; __device__ __forceinline__ void gemm_phase(PG8_LAS unsigned char* lds, const Gemm g, const Sched& S, const Epi& E) {
;     ...
;             PG8_LDB(B0, 1, 0); PG8_LDB(B1, 1, 1); PG8_SCHED; PG8_LDA(At, 1, 0); PG8_STAGE(PG8_SA(0, 1), a2 + hstepA, voffA);
;             PG8_WAIT_V(8); PG8_WAIT_L(0); PG8_BAR; PG8_MMA(0, 0, At, B0); PG8_MMA(0, 1, At, B1); PG8_BAR; PG8_SCHED;
;             PG8_LDA(At, 1, 1); PG8_STAGE(PG8_SB(1, 0), b3, voffB); PG8_STAGE(PG8_SB(1, 1), b3 + hstepB, voffB); PG8_STAGE(PG8_SA(1, 0), a3, voffA);
;             PG8_WAIT_V(8); PG8_WAIT_L(0); PG8_BAR; PG8_MMA(1, 0, At, B0); PG8_MMA(1, 1, At, B1); PG8_BAR; PG8_SCHED;
;         }
;         if constexpr (ALIGN_EPI) { if (wr == 0) PG8_BAR; }
	s_add_i32 s67, 0, 0x18000
	v_add_u32_e32 v155, s67, v1
	s_add_i32 s68, 0, 0x1c000
	ds_read_b128 v[146:149], v155
	ds_read_b128 v[156:159], v155 offset:1024
	ds_read_b128 v[160:163], v155 offset:2048
	ds_read_b128 v[164:167], v155 offset:3072
	v_add_u32_e32 v155, s68, v1
	ds_read_b128 v[168:171], v155
	ds_read_b128 v[172:175], v155 offset:1024
	ds_read_b128 v[176:179], v155 offset:2048
	ds_read_b128 v[180:183], v155 offset:3072
	s_add_u32 s38, s38, 0x100000
	s_addc_u32 s39, s39, 0
	s_mov_b32 m0, s45
	ds_read_b128 v[184:187], v154 offset:32768
	ds_read_b128 v[188:191], v154 offset:33792
	ds_read_b128 v[192:195], v154 offset:34816
	ds_read_b128 v[196:199], v154 offset:35840
	ds_read_b128 v[200:203], v154 offset:36864
	ds_read_b128 v[204:207], v154 offset:37888
	ds_read_b128 v[208:211], v154 offset:38912
	ds_read_b128 v[212:215], v154 offset:39936
	global_load_lds_dwordx4 v130, s[38:39]
	s_mov_b32 m0, s46
	s_nop 0
	global_load_lds_dwordx4 v134, s[38:39]
	s_waitcnt vmcnt(8)
	s_waitcnt lgkmcnt(0)
	s_barrier
	s_waitcnt lgkmcnt(0)
	v_mfma_f32_16x16x32_bf16 v[126:129], v[146:149], v[184:187], v[126:129]
	v_mfma_f32_16x16x32_bf16 v[122:125], v[160:163], v[184:187], v[122:125]
	v_mfma_f32_16x16x32_bf16 v[114:117], v[146:149], v[192:195], v[114:117]
	v_mfma_f32_16x16x32_bf16 v[106:109], v[160:163], v[192:195], v[106:109]
	v_mfma_f32_16x16x32_bf16 v[98:101], v[146:149], v[200:203], v[98:101]
	v_mfma_f32_16x16x32_bf16 v[90:93], v[160:163], v[200:203], v[90:93]
	v_mfma_f32_16x16x32_bf16 v[82:85], v[146:149], v[208:211], v[82:85]
	v_mfma_f32_16x16x32_bf16 v[74:77], v[160:163], v[208:211], v[74:77]
	v_mfma_f32_16x16x32_bf16 v[126:129], v[156:159], v[188:191], v[126:129]
	v_mfma_f32_16x16x32_bf16 v[122:125], v[164:167], v[188:191], v[122:125]
	v_mfma_f32_16x16x32_bf16 v[114:117], v[156:159], v[196:199], v[114:117]
	v_mfma_f32_16x16x32_bf16 v[106:109], v[164:167], v[196:199], v[106:109]
	v_mfma_f32_16x16x32_bf16 v[98:101], v[156:159], v[204:207], v[98:101]
	v_mfma_f32_16x16x32_bf16 v[90:93], v[164:167], v[204:207], v[90:93]
	v_mfma_f32_16x16x32_bf16 v[82:85], v[156:159], v[212:215], v[82:85]
	v_mfma_f32_16x16x32_bf16 v[74:77], v[164:167], v[212:215], v[74:77]
	v_mfma_f32_16x16x32_bf16 v[118:121], v[168:171], v[184:187], v[118:121]
	v_mfma_f32_16x16x32_bf16 v[110:113], v[176:179], v[184:187], v[110:113]
	v_mfma_f32_16x16x32_bf16 v[102:105], v[168:171], v[192:195], v[102:105]
	v_mfma_f32_16x16x32_bf16 v[94:97], v[176:179], v[192:195], v[94:97]
	v_mfma_f32_16x16x32_bf16 v[86:89], v[168:171], v[200:203], v[86:89]
	v_mfma_f32_16x16x32_bf16 v[78:81], v[176:179], v[200:203], v[78:81]
	v_mfma_f32_16x16x32_bf16 v[70:73], v[168:171], v[208:211], v[70:73]
	v_mfma_f32_16x16x32_bf16 v[66:69], v[176:179], v[208:211], v[66:69]
	v_mfma_f32_16x16x32_bf16 v[118:121], v[172:175], v[188:191], v[118:121]
	v_mfma_f32_16x16x32_bf16 v[110:113], v[180:183], v[188:191], v[110:113]
	v_mfma_f32_16x16x32_bf16 v[102:105], v[172:175], v[196:199], v[102:105]
	v_mfma_f32_16x16x32_bf16 v[94:97], v[180:183], v[196:199], v[94:97]
	v_mfma_f32_16x16x32_bf16 v[86:89], v[172:175], v[204:207], v[86:89]
	v_mfma_f32_16x16x32_bf16 v[78:81], v[180:183], v[204:207], v[78:81]
	v_mfma_f32_16x16x32_bf16 v[70:73], v[172:175], v[212:215], v[70:73]
	v_mfma_f32_16x16x32_bf16 v[66:69], v[180:183], v[212:215], v[66:69]
	s_barrier
	s_add_i32 s38, s67, s43
	s_mov_b32 m0, s38
	ds_read_b128 v[184:187], v154 offset:49152
	ds_read_b128 v[188:191], v154 offset:50176
	ds_read_b128 v[192:195], v154 offset:51200
	ds_read_b128 v[196:199], v154 offset:52224
	ds_read_b128 v[200:203], v154 offset:53248
	ds_read_b128 v[204:207], v154 offset:54272
	ds_read_b128 v[208:211], v154 offset:55296
	ds_read_b128 v[212:215], v154 offset:56320
	global_load_lds_dwordx4 v132, s[98:99]
	s_add_i32 m0, s38, 0x2000
	s_add_u32 s36, s36, 0x100080
	s_addc_u32 s37, s37, 0
	s_add_i32 s38, s68, s43
	global_load_lds_dwordx4 v136, s[98:99]
	s_mov_b32 m0, s38
	s_nop 0
	global_load_lds_dwordx4 v132, s[36:37]
	s_add_i32 m0, s38, 0x2000
	s_nop 0
	global_load_lds_dwordx4 v136, s[36:37]
	s_mov_b32 m0, s48
	s_nop 0
	global_load_lds_dwordx4 v130, s[100:101]
	s_mov_b32 m0, s49
	s_nop 0
	global_load_lds_dwordx4 v134, s[100:101]
	s_waitcnt vmcnt(8)
	s_waitcnt lgkmcnt(0)
	s_barrier
	s_waitcnt lgkmcnt(0)
	v_mfma_f32_16x16x32_bf16 v[62:65], v[146:149], v[184:187], v[62:65]
	v_mfma_f32_16x16x32_bf16 v[58:61], v[160:163], v[184:187], v[58:61]
	v_mfma_f32_16x16x32_bf16 v[50:53], v[146:149], v[192:195], v[50:53]
	v_mfma_f32_16x16x32_bf16 v[42:45], v[160:163], v[192:195], v[42:45]
	v_mfma_f32_16x16x32_bf16 v[34:37], v[146:149], v[200:203], v[34:37]
	v_mfma_f32_16x16x32_bf16 v[26:29], v[160:163], v[200:203], v[26:29]
	v_mfma_f32_16x16x32_bf16 v[18:21], v[146:149], v[208:211], v[18:21]
	v_mfma_f32_16x16x32_bf16 v[10:13], v[160:163], v[208:211], v[10:13]
	v_mfma_f32_16x16x32_bf16 v[62:65], v[156:159], v[188:191], v[62:65]
	v_mfma_f32_16x16x32_bf16 v[58:61], v[164:167], v[188:191], v[58:61]
	v_mfma_f32_16x16x32_bf16 v[50:53], v[156:159], v[196:199], v[50:53]
	v_mfma_f32_16x16x32_bf16 v[42:45], v[164:167], v[196:199], v[42:45]
	v_mfma_f32_16x16x32_bf16 v[34:37], v[156:159], v[204:207], v[34:37]
	v_mfma_f32_16x16x32_bf16 v[26:29], v[164:167], v[204:207], v[26:29]
	v_mfma_f32_16x16x32_bf16 v[18:21], v[156:159], v[212:215], v[18:21]
	v_mfma_f32_16x16x32_bf16 v[10:13], v[164:167], v[212:215], v[10:13]
	v_mfma_f32_16x16x32_bf16 v[54:57], v[168:171], v[184:187], v[54:57]
	v_mfma_f32_16x16x32_bf16 v[46:49], v[176:179], v[184:187], v[46:49]
	v_mfma_f32_16x16x32_bf16 v[38:41], v[168:171], v[192:195], v[38:41]
	v_mfma_f32_16x16x32_bf16 v[30:33], v[176:179], v[192:195], v[30:33]
	v_mfma_f32_16x16x32_bf16 v[22:25], v[168:171], v[200:203], v[22:25]
	v_mfma_f32_16x16x32_bf16 v[14:17], v[176:179], v[200:203], v[14:17]
	v_mfma_f32_16x16x32_bf16 v[6:9], v[168:171], v[208:211], v[6:9]
	v_mfma_f32_16x16x32_bf16 v[2:5], v[176:179], v[208:211], v[2:5]
	v_mfma_f32_16x16x32_bf16 v[54:57], v[172:175], v[188:191], v[54:57]
	v_mfma_f32_16x16x32_bf16 v[46:49], v[180:183], v[188:191], v[46:49]
	v_mfma_f32_16x16x32_bf16 v[38:41], v[172:175], v[196:199], v[38:41]
	v_mfma_f32_16x16x32_bf16 v[30:33], v[180:183], v[196:199], v[30:33]
	v_mfma_f32_16x16x32_bf16 v[22:25], v[172:175], v[204:207], v[22:25]
	v_mfma_f32_16x16x32_bf16 v[14:17], v[180:183], v[204:207], v[14:17]
	v_mfma_f32_16x16x32_bf16 v[6:9], v[172:175], v[212:215], v[6:9]
	v_mfma_f32_16x16x32_bf16 v[2:5], v[180:183], v[212:215], v[2:5]
	s_barrier
	s_add_i32 s66, s66, 2
	s_add_u32 s34, s34, 0x100
	s_addc_u32 s35, s35, 0
	s_add_u32 s64, s64, 0x100
	s_addc_u32 s65, s65, 0
	s_cmp_gt_u32 s66, 61
	s_cbranch_scc0 .LBB0_1423
	s_and_b64 vcc, exec, s[14:15]
	s_cbranch_vccz .LBB0_1426
	s_barrier
